# epiresid_epilogue_vmcnt_recounted_with_asm_stores
# speedup vs baseline: 1.0166x; 1.0033x over previous
.LBB0_887:
	v_lshl_add_u32 v182, s26, 8, v169
	v_lshl_or_b32 v180, s51, 8, v192
	v_ashrrev_i32_e32 v183, 31, v182
	v_ashrrev_i32_e32 v181, 31, v180
	v_lshl_add_u64 v[184:185], v[180:181], 2, s[4:5]
	v_lshlrev_b64 v[128:129], 12, v[182:183]
	v_lshl_add_u64 v[128:129], v[184:185], 0, v[128:129]
	global_load_dwordx4 v[198:201], v[128:129], off offset:528
	global_load_dwordx4 v[202:205], v[128:129], off offset:512
	v_lshlrev_b64 v[128:129], 10, v[182:183]
	v_lshl_add_u64 v[188:189], v[128:129], 0, v[180:181]
	v_lshl_add_u64 v[128:129], v[188:189], 2, s[4:5]
	global_load_dwordx4 v[206:209], v[128:129], off
	global_load_dwordx4 v[210:213], v[128:129], off offset:16
	v_or_b32_e32 v190, 16, v182
	v_or_b32_e32 v186, 32, v182
	v_ashrrev_i32_e32 v191, 31, v190
	v_ashrrev_i32_e32 v187, 31, v186
	v_lshlrev_b64 v[128:129], 12, v[190:191]
	v_lshlrev_b64 v[130:131], 12, v[186:187]
	v_lshl_add_u64 v[128:129], v[184:185], 0, v[128:129]
	v_lshl_add_u64 v[132:133], v[184:185], 0, v[130:131]
	global_load_dwordx4 v[152:155], v[128:129], off offset:16
	global_load_dwordx4 v[156:159], v[128:129], off
	global_load_dwordx4 v[144:147], v[128:129], off offset:528
	global_load_dwordx4 v[148:151], v[128:129], off offset:512
	global_load_dwordx4 v[136:139], v[132:133], off offset:16
	global_load_dwordx4 v[140:143], v[132:133], off
	s_nop 0
	global_load_dwordx4 v[128:131], v[132:133], off offset:528
	s_nop 0
	global_load_dwordx4 v[132:135], v[132:133], off offset:512
	v_and_b32_e32 v214, 64, v196
	v_xor_b32_e32 v197, 16, v196
	v_add_u32_e32 v214, 64, v214
	v_cmp_lt_i32_e32 vcc, v197, v214
	v_xor_b32_e32 v215, 32, v196
	v_lshl_add_u64 v[188:189], v[188:189], 1, s[12:13]
	v_cndmask_b32_e32 v197, v196, v197, vcc
	v_lshlrev_b32_e32 v197, 2, v197
	v_cmp_lt_i32_e32 vcc, v215, v214
	s_waitcnt vmcnt(8)
	v_pk_add_f32 v[200:201], v[114:115], v[200:201]
	v_pk_add_f32 v[204:205], v[118:119], v[204:205]
	v_pk_add_f32 v[202:203], v[116:117], v[202:203]
	v_pk_add_f32 v[112:113], v[112:113], v[198:199]
	v_pk_add_f32 v[126:127], v[126:127], v[208:209]
	v_pk_add_f32 v[124:125], v[124:125], v[206:207]
	v_pk_add_f32 v[122:123], v[122:123], v[212:213]
	v_pk_add_f32 v[120:121], v[120:121], v[210:211]
	v_mul_f32_e32 v119, v203, v203
	v_mul_f32_e32 v198, v205, v205
	v_mul_f32_e32 v199, v113, v113
	v_mul_f32_e32 v206, v201, v201
	v_cvt_pk_bf16_f32 v114, v202, v203
	v_cvt_pk_bf16_f32 v115, v204, v205
	v_cvt_pk_bf16_f32 v116, v112, v113
	v_cvt_pk_bf16_f32 v117, v200, v201
	v_mul_f32_e32 v113, v125, v125
	v_mul_f32_e32 v201, v127, v127
	v_mul_f32_e32 v203, v121, v121
	v_mul_f32_e32 v205, v123, v123
	v_fmac_f32_e32 v119, v202, v202
	v_fmac_f32_e32 v198, v204, v204
	v_fmac_f32_e32 v199, v112, v112
	v_fmac_f32_e32 v206, v200, v200
	v_fmac_f32_e32 v113, v124, v124
	v_fmac_f32_e32 v201, v126, v126
	v_fmac_f32_e32 v203, v120, v120
	v_fmac_f32_e32 v205, v122, v122
	v_cvt_pk_bf16_f32 v118, v124, v125
	v_add_f32_e32 v112, v119, v198
	v_add_f32_e32 v119, v199, v206
	v_add_f32_e32 v113, v113, v201
	v_add_f32_e32 v124, v203, v205
	v_add_f32_e32 v112, v112, v119
	v_add_f32_e32 v113, v113, v124
	v_add_f32_e32 v112, v113, v112
	ds_bpermute_b32 v113, v197, v112
	v_cndmask_b32_e32 v216, v196, v215, vcc
	v_lshlrev_b32_e32 v198, 2, v216
	v_cvt_pk_bf16_f32 v119, v126, v127
	v_cvt_pk_bf16_f32 v120, v120, v121
	s_waitcnt lgkmcnt(0)
	v_add_f32_e32 v112, v112, v113
	ds_bpermute_b32 v113, v198, v112
	v_cvt_pk_bf16_f32 v121, v122, v123
	global_store_dwordx4 v[188:189], v[118:121], off sc1
	s_nop 1
	v_lshl_add_u64 v[214:215], v[188:189], 0, s[14:15]
	global_store_dwordx4 v[214:215], v[114:117], off sc1
	s_nop 1
	s_and_saveexec_b64 s[0:1], s[6:7]
	s_cbranch_execz .LBB0_889
	s_waitcnt lgkmcnt(0)
	v_add_f32_e32 v114, v112, v113
	s_lshl_b32 s26, s51, 2
	v_lshlrev_b64 v[112:113], 6, v[182:183]
	s_ashr_i32 s27, s26, 31
	v_lshl_add_u64 v[112:113], s[18:19], 0, v[112:113]
	v_lshl_add_u64 v[112:113], s[26:27], 2, v[112:113]
	s_lshl_b32 s10, s45, 2
	v_lshl_add_u64 v[112:113], v[112:113], 0, s[10:11]
	global_store_dword v[112:113], v114, off
.LBB0_889:
	s_or_b64 exec, exec, s[0:1]
	v_or_b32_e32 v188, 48, v182
	v_ashrrev_i32_e32 v189, 31, v188
	s_waitcnt lgkmcnt(0)
	v_lshlrev_b64 v[112:113], 12, v[188:189]
	v_lshl_add_u64 v[116:117], v[184:185], 0, v[112:113]
	global_load_dwordx4 v[120:123], v[116:117], off offset:16
	global_load_dwordx4 v[124:127], v[116:117], off
	global_load_dwordx4 v[112:115], v[116:117], off offset:528
	s_nop 0
	global_load_dwordx4 v[116:119], v[116:117], off offset:512
	s_waitcnt vmcnt(11)
	v_pk_add_f32 v[110:111], v[110:111], v[158:159]
	v_pk_add_f32 v[108:109], v[108:109], v[156:157]
	v_pk_add_f32 v[154:155], v[106:107], v[154:155]
	v_pk_add_f32 v[106:107], v[104:105], v[152:153]
	v_mul_f32_e32 v104, v109, v109
	v_mul_f32_e32 v105, v111, v111
	v_fmac_f32_e32 v104, v108, v108
	v_fmac_f32_e32 v105, v110, v110
	v_add_f32_e32 v104, v104, v105
	v_mul_f32_e32 v105, v107, v107
	v_mul_f32_e32 v152, v155, v155
	v_fmac_f32_e32 v105, v106, v106
	v_fmac_f32_e32 v152, v154, v154
	v_lshlrev_b64 v[200:201], 10, v[190:191]
	v_add_f32_e32 v105, v105, v152
	v_lshl_add_u64 v[200:201], v[200:201], 0, v[180:181]
	v_add_f32_e32 v152, v104, v105
	v_cvt_pk_bf16_f32 v104, v108, v109
	v_cvt_pk_bf16_f32 v105, v110, v111
	v_pk_add_f32 v[102:103], v[102:103], v[150:151]
	v_pk_add_f32 v[100:101], v[100:101], v[148:149]
	v_cvt_pk_bf16_f32 v106, v106, v107
	v_cvt_pk_bf16_f32 v107, v154, v155
	v_lshl_add_u64 v[108:109], v[200:201], 1, s[12:13]
	global_store_dwordx4 v[108:109], v[104:107], off sc1
	s_nop 1
	v_pk_add_f32 v[104:105], v[98:99], v[146:147]
	v_mul_f32_e32 v98, v101, v101
	v_mul_f32_e32 v99, v103, v103
	v_pk_add_f32 v[96:97], v[96:97], v[144:145]
	v_fmac_f32_e32 v98, v100, v100
	v_fmac_f32_e32 v99, v102, v102
	v_add_f32_e32 v98, v98, v99
	v_mul_f32_e32 v99, v97, v97
	v_mul_f32_e32 v106, v105, v105
	v_fmac_f32_e32 v99, v96, v96
	v_fmac_f32_e32 v106, v104, v104
	v_add_f32_e32 v99, v99, v106
	v_add_f32_e32 v98, v98, v99
	v_add_f32_e32 v106, v152, v98
	ds_bpermute_b32 v107, v197, v106
	v_cvt_pk_bf16_f32 v98, v100, v101
	v_cvt_pk_bf16_f32 v100, v96, v97
	v_cvt_pk_bf16_f32 v99, v102, v103
	v_cvt_pk_bf16_f32 v101, v104, v105
	s_waitcnt lgkmcnt(0)
	v_add_f32_e32 v96, v106, v107
	ds_bpermute_b32 v97, v198, v96
	v_lshl_add_u64 v[102:103], v[108:109], 0, s[14:15]
	global_store_dwordx4 v[102:103], v[98:101], off sc1
	s_nop 1
	s_and_saveexec_b64 s[0:1], s[6:7]
	s_cbranch_execz .LBB0_891
	s_waitcnt lgkmcnt(0)
	v_add_f32_e32 v98, v96, v97
	s_lshl_b32 s26, s51, 2
	v_lshlrev_b64 v[96:97], 6, v[190:191]
	s_ashr_i32 s27, s26, 31
	v_lshl_add_u64 v[96:97], s[18:19], 0, v[96:97]
	v_lshl_add_u64 v[96:97], s[26:27], 2, v[96:97]
	s_lshl_b32 s10, s45, 2
	v_lshl_add_u64 v[96:97], v[96:97], 0, s[10:11]
	global_store_dword v[96:97], v98, off
.LBB0_891:
	s_or_b64 exec, exec, s[0:1]
	v_add_u32_e32 v144, 0x80, v182
	v_ashrrev_i32_e32 v145, 31, v144
	s_waitcnt lgkmcnt(0)
	v_lshlrev_b64 v[96:97], 12, v[144:145]
	v_lshl_add_u64 v[100:101], v[184:185], 0, v[96:97]
	global_load_dwordx4 v[104:107], v[100:101], off offset:16
	global_load_dwordx4 v[108:111], v[100:101], off
	global_load_dwordx4 v[96:99], v[100:101], off offset:528
	s_nop 0
	global_load_dwordx4 v[100:103], v[100:101], off offset:512
	s_waitcnt vmcnt(14)
	v_pk_add_f32 v[94:95], v[94:95], v[142:143]
	v_pk_add_f32 v[92:93], v[92:93], v[140:141]
	v_pk_add_f32 v[138:139], v[90:91], v[138:139]
	v_pk_add_f32 v[90:91], v[88:89], v[136:137]
	v_mul_f32_e32 v88, v93, v93
	v_mul_f32_e32 v89, v95, v95
	v_fmac_f32_e32 v88, v92, v92
	v_fmac_f32_e32 v89, v94, v94
	v_add_f32_e32 v88, v88, v89
	v_mul_f32_e32 v89, v91, v91
	v_mul_f32_e32 v136, v139, v139
	v_fmac_f32_e32 v89, v90, v90
	v_fmac_f32_e32 v136, v138, v138
	v_lshlrev_b64 v[146:147], 10, v[186:187]
	v_add_f32_e32 v89, v89, v136
	v_lshl_add_u64 v[146:147], v[146:147], 0, v[180:181]
	v_add_f32_e32 v136, v88, v89
	v_cvt_pk_bf16_f32 v88, v92, v93
	v_cvt_pk_bf16_f32 v89, v94, v95
	v_pk_add_f32 v[86:87], v[86:87], v[134:135]
	v_pk_add_f32 v[84:85], v[84:85], v[132:133]
	v_cvt_pk_bf16_f32 v90, v90, v91
	v_cvt_pk_bf16_f32 v91, v138, v139
	v_lshl_add_u64 v[92:93], v[146:147], 1, s[12:13]
	global_store_dwordx4 v[92:93], v[88:91], off sc1
	s_nop 1
	v_pk_add_f32 v[88:89], v[82:83], v[130:131]
	v_mul_f32_e32 v82, v85, v85
	v_mul_f32_e32 v83, v87, v87
	v_pk_add_f32 v[80:81], v[80:81], v[128:129]
	v_fmac_f32_e32 v82, v84, v84
	v_fmac_f32_e32 v83, v86, v86
	v_add_f32_e32 v82, v82, v83
	v_mul_f32_e32 v83, v81, v81
	v_mul_f32_e32 v90, v89, v89
	v_fmac_f32_e32 v83, v80, v80
	v_fmac_f32_e32 v90, v88, v88
	v_add_f32_e32 v83, v83, v90
	v_add_f32_e32 v82, v82, v83
	v_add_f32_e32 v90, v136, v82
	ds_bpermute_b32 v91, v197, v90
	v_cvt_pk_bf16_f32 v82, v84, v85
	v_cvt_pk_bf16_f32 v84, v80, v81
	v_cvt_pk_bf16_f32 v83, v86, v87
	v_cvt_pk_bf16_f32 v85, v88, v89
	s_waitcnt lgkmcnt(0)
	v_add_f32_e32 v80, v90, v91
	ds_bpermute_b32 v81, v198, v80
	v_lshl_add_u64 v[86:87], v[92:93], 0, s[14:15]
	global_store_dwordx4 v[86:87], v[82:85], off sc1
	s_nop 1
	s_and_saveexec_b64 s[0:1], s[6:7]
	s_cbranch_execz .LBB0_893
	s_waitcnt lgkmcnt(0)
	v_add_f32_e32 v82, v80, v81
	s_lshl_b32 s26, s51, 2
	v_lshlrev_b64 v[80:81], 6, v[186:187]
	s_ashr_i32 s27, s26, 31
	v_lshl_add_u64 v[80:81], s[18:19], 0, v[80:81]
	v_lshl_add_u64 v[80:81], s[26:27], 2, v[80:81]
	s_lshl_b32 s10, s45, 2
	v_lshl_add_u64 v[80:81], v[80:81], 0, s[10:11]
	global_store_dword v[80:81], v82, off
.LBB0_893:
	s_or_b64 exec, exec, s[0:1]
	v_add_u32_e32 v128, 0x90, v182
	v_ashrrev_i32_e32 v129, 31, v128
	s_waitcnt lgkmcnt(0)
	v_lshlrev_b64 v[80:81], 12, v[128:129]
	v_lshl_add_u64 v[84:85], v[184:185], 0, v[80:81]
	global_load_dwordx4 v[88:91], v[84:85], off offset:16
	global_load_dwordx4 v[92:95], v[84:85], off
	global_load_dwordx4 v[80:83], v[84:85], off offset:528
	s_nop 0
	global_load_dwordx4 v[84:87], v[84:85], off offset:512
	s_waitcnt vmcnt(14)
	v_pk_add_f32 v[78:79], v[78:79], v[126:127]
	v_pk_add_f32 v[76:77], v[76:77], v[124:125]
	v_pk_add_f32 v[122:123], v[74:75], v[122:123]
	v_pk_add_f32 v[74:75], v[72:73], v[120:121]
	v_mul_f32_e32 v72, v77, v77
	v_mul_f32_e32 v73, v79, v79
	v_fmac_f32_e32 v72, v76, v76
	v_fmac_f32_e32 v73, v78, v78
	v_add_f32_e32 v72, v72, v73
	v_mul_f32_e32 v73, v75, v75
	v_mul_f32_e32 v120, v123, v123
	v_fmac_f32_e32 v73, v74, v74
	v_fmac_f32_e32 v120, v122, v122
	v_lshlrev_b64 v[130:131], 10, v[188:189]
	v_add_f32_e32 v73, v73, v120
	v_lshl_add_u64 v[130:131], v[130:131], 0, v[180:181]
	v_add_f32_e32 v120, v72, v73
	v_cvt_pk_bf16_f32 v72, v76, v77
	v_cvt_pk_bf16_f32 v73, v78, v79
	s_waitcnt vmcnt(14)
	v_pk_add_f32 v[70:71], v[70:71], v[118:119]
	v_pk_add_f32 v[68:69], v[68:69], v[116:117]
	v_cvt_pk_bf16_f32 v74, v74, v75
	v_cvt_pk_bf16_f32 v75, v122, v123
	v_lshl_add_u64 v[76:77], v[130:131], 1, s[12:13]
	global_store_dwordx4 v[76:77], v[72:75], off sc1
	s_nop 1
	v_pk_add_f32 v[72:73], v[66:67], v[114:115]
	v_mul_f32_e32 v66, v69, v69
	v_mul_f32_e32 v67, v71, v71
	v_pk_add_f32 v[64:65], v[64:65], v[112:113]
	v_fmac_f32_e32 v66, v68, v68
	v_fmac_f32_e32 v67, v70, v70
	v_add_f32_e32 v66, v66, v67
	v_mul_f32_e32 v67, v65, v65
	v_mul_f32_e32 v74, v73, v73
	v_fmac_f32_e32 v67, v64, v64
	v_fmac_f32_e32 v74, v72, v72
	v_add_f32_e32 v67, v67, v74
	v_add_f32_e32 v66, v66, v67
	v_add_f32_e32 v74, v120, v66
	ds_bpermute_b32 v75, v197, v74
	v_cvt_pk_bf16_f32 v66, v68, v69
	v_cvt_pk_bf16_f32 v68, v64, v65
	v_cvt_pk_bf16_f32 v67, v70, v71
	v_cvt_pk_bf16_f32 v69, v72, v73
	s_waitcnt lgkmcnt(0)
	v_add_f32_e32 v64, v74, v75
	ds_bpermute_b32 v65, v198, v64
	v_lshl_add_u64 v[70:71], v[76:77], 0, s[14:15]
	global_store_dwordx4 v[70:71], v[66:69], off sc1
	s_nop 1
	s_and_saveexec_b64 s[0:1], s[6:7]
	s_cbranch_execz .LBB0_895
	s_waitcnt lgkmcnt(0)
	v_add_f32_e32 v66, v64, v65
	s_lshl_b32 s26, s51, 2
	v_lshlrev_b64 v[64:65], 6, v[188:189]
	s_ashr_i32 s27, s26, 31
	v_lshl_add_u64 v[64:65], s[18:19], 0, v[64:65]
	v_lshl_add_u64 v[64:65], s[26:27], 2, v[64:65]
	s_lshl_b32 s10, s45, 2
	v_lshl_add_u64 v[64:65], v[64:65], 0, s[10:11]
	global_store_dword v[64:65], v66, off
.LBB0_895:
	s_or_b64 exec, exec, s[0:1]
	v_add_u32_e32 v112, 0xa0, v182
	v_ashrrev_i32_e32 v113, 31, v112
	s_waitcnt lgkmcnt(0)
	v_lshlrev_b64 v[64:65], 12, v[112:113]
	v_lshl_add_u64 v[68:69], v[184:185], 0, v[64:65]
	global_load_dwordx4 v[72:75], v[68:69], off offset:16
	global_load_dwordx4 v[76:79], v[68:69], off
	global_load_dwordx4 v[64:67], v[68:69], off offset:528
	s_nop 0
	global_load_dwordx4 v[68:71], v[68:69], off offset:512
	s_waitcnt vmcnt(14)
	v_pk_add_f32 v[62:63], v[62:63], v[110:111]
	v_pk_add_f32 v[60:61], v[60:61], v[108:109]
	v_pk_add_f32 v[106:107], v[58:59], v[106:107]
	v_pk_add_f32 v[58:59], v[56:57], v[104:105]
	v_mul_f32_e32 v56, v61, v61
	v_mul_f32_e32 v57, v63, v63
	v_fmac_f32_e32 v56, v60, v60
	v_fmac_f32_e32 v57, v62, v62
	v_add_f32_e32 v56, v56, v57
	v_mul_f32_e32 v57, v59, v59
	v_mul_f32_e32 v104, v107, v107
	v_fmac_f32_e32 v57, v58, v58
	v_fmac_f32_e32 v104, v106, v106
	v_lshlrev_b64 v[114:115], 10, v[144:145]
	v_add_f32_e32 v57, v57, v104
	v_lshl_add_u64 v[114:115], v[114:115], 0, v[180:181]
	v_add_f32_e32 v104, v56, v57
	v_cvt_pk_bf16_f32 v56, v60, v61
	v_cvt_pk_bf16_f32 v57, v62, v63
	s_waitcnt vmcnt(14)
	v_pk_add_f32 v[54:55], v[54:55], v[102:103]
	v_pk_add_f32 v[52:53], v[52:53], v[100:101]
	v_cvt_pk_bf16_f32 v58, v58, v59
	v_cvt_pk_bf16_f32 v59, v106, v107
	v_lshl_add_u64 v[60:61], v[114:115], 1, s[12:13]
	global_store_dwordx4 v[60:61], v[56:59], off sc1
	s_nop 1
	v_pk_add_f32 v[56:57], v[50:51], v[98:99]
	v_mul_f32_e32 v50, v53, v53
	v_mul_f32_e32 v51, v55, v55
	v_pk_add_f32 v[48:49], v[48:49], v[96:97]
	v_fmac_f32_e32 v50, v52, v52
	v_fmac_f32_e32 v51, v54, v54
	v_add_f32_e32 v50, v50, v51
	v_mul_f32_e32 v51, v49, v49
	v_mul_f32_e32 v58, v57, v57
	v_fmac_f32_e32 v51, v48, v48
	v_fmac_f32_e32 v58, v56, v56
	v_add_f32_e32 v51, v51, v58
	v_add_f32_e32 v50, v50, v51
	v_add_f32_e32 v58, v104, v50
	ds_bpermute_b32 v59, v197, v58
	v_cvt_pk_bf16_f32 v50, v52, v53
	v_cvt_pk_bf16_f32 v52, v48, v49
	v_cvt_pk_bf16_f32 v51, v54, v55
	v_cvt_pk_bf16_f32 v53, v56, v57
	s_waitcnt lgkmcnt(0)
	v_add_f32_e32 v48, v58, v59
	ds_bpermute_b32 v49, v198, v48
	v_lshl_add_u64 v[54:55], v[60:61], 0, s[14:15]
	global_store_dwordx4 v[54:55], v[50:53], off sc1
	s_nop 1
	s_and_saveexec_b64 s[0:1], s[6:7]
	s_cbranch_execz .LBB0_897
	s_waitcnt lgkmcnt(0)
	v_add_f32_e32 v50, v48, v49
	s_lshl_b32 s26, s51, 2
	v_lshlrev_b64 v[48:49], 6, v[144:145]
	s_ashr_i32 s27, s26, 31
	v_lshl_add_u64 v[48:49], s[18:19], 0, v[48:49]
	v_lshl_add_u64 v[48:49], s[26:27], 2, v[48:49]
	s_lshl_b32 s10, s45, 2
	v_lshl_add_u64 v[48:49], v[48:49], 0, s[10:11]
	global_store_dword v[48:49], v50, off
.LBB0_897:
	s_or_b64 exec, exec, s[0:1]
	v_add_u32_e32 v96, 0xb0, v182
	v_ashrrev_i32_e32 v97, 31, v96
	s_waitcnt lgkmcnt(0)
	v_lshlrev_b64 v[48:49], 12, v[96:97]
	v_lshl_add_u64 v[52:53], v[184:185], 0, v[48:49]
	global_load_dwordx4 v[56:59], v[52:53], off offset:16
	global_load_dwordx4 v[60:63], v[52:53], off
	global_load_dwordx4 v[48:51], v[52:53], off offset:528
	s_nop 0
	global_load_dwordx4 v[52:55], v[52:53], off offset:512
	s_waitcnt vmcnt(14)
	v_pk_add_f32 v[46:47], v[46:47], v[94:95]
	v_pk_add_f32 v[44:45], v[44:45], v[92:93]
	v_pk_add_f32 v[90:91], v[42:43], v[90:91]
	v_pk_add_f32 v[42:43], v[40:41], v[88:89]
	v_mul_f32_e32 v40, v45, v45
	v_mul_f32_e32 v41, v47, v47
	v_fmac_f32_e32 v40, v44, v44
	v_fmac_f32_e32 v41, v46, v46
	v_add_f32_e32 v40, v40, v41
	v_mul_f32_e32 v41, v43, v43
	v_mul_f32_e32 v88, v91, v91
	v_fmac_f32_e32 v41, v42, v42
	v_fmac_f32_e32 v88, v90, v90
	v_lshlrev_b64 v[98:99], 10, v[128:129]
	v_add_f32_e32 v41, v41, v88
	v_lshl_add_u64 v[98:99], v[98:99], 0, v[180:181]
	v_add_f32_e32 v88, v40, v41
	v_cvt_pk_bf16_f32 v40, v44, v45
	v_cvt_pk_bf16_f32 v41, v46, v47
	s_waitcnt vmcnt(14)
	v_pk_add_f32 v[38:39], v[38:39], v[86:87]
	v_pk_add_f32 v[36:37], v[36:37], v[84:85]
	v_cvt_pk_bf16_f32 v42, v42, v43
	v_cvt_pk_bf16_f32 v43, v90, v91
	v_lshl_add_u64 v[44:45], v[98:99], 1, s[12:13]
	global_store_dwordx4 v[44:45], v[40:43], off sc1
	s_nop 1
	v_pk_add_f32 v[40:41], v[34:35], v[82:83]
	v_mul_f32_e32 v34, v37, v37
	v_mul_f32_e32 v35, v39, v39
	v_pk_add_f32 v[32:33], v[32:33], v[80:81]
	v_fmac_f32_e32 v34, v36, v36
	v_fmac_f32_e32 v35, v38, v38
	v_add_f32_e32 v34, v34, v35
	v_mul_f32_e32 v35, v33, v33
	v_mul_f32_e32 v42, v41, v41
	v_fmac_f32_e32 v35, v32, v32
	v_fmac_f32_e32 v42, v40, v40
	v_add_f32_e32 v35, v35, v42
	v_add_f32_e32 v34, v34, v35
	v_add_f32_e32 v42, v88, v34
	ds_bpermute_b32 v43, v197, v42
	v_cvt_pk_bf16_f32 v34, v36, v37
	v_cvt_pk_bf16_f32 v36, v32, v33
	v_cvt_pk_bf16_f32 v35, v38, v39
	v_cvt_pk_bf16_f32 v37, v40, v41
	s_waitcnt lgkmcnt(0)
	v_add_f32_e32 v32, v42, v43
	ds_bpermute_b32 v33, v198, v32
	v_lshl_add_u64 v[38:39], v[44:45], 0, s[14:15]
	global_store_dwordx4 v[38:39], v[34:37], off sc1
	s_nop 1
	s_and_saveexec_b64 s[0:1], s[6:7]
	s_cbranch_execz .LBB0_899
	s_waitcnt lgkmcnt(0)
	v_add_f32_e32 v34, v32, v33
	s_lshl_b32 s26, s51, 2
	v_lshlrev_b64 v[32:33], 6, v[128:129]
	s_ashr_i32 s27, s26, 31
	v_lshl_add_u64 v[32:33], s[18:19], 0, v[32:33]
	v_lshl_add_u64 v[32:33], s[26:27], 2, v[32:33]
	s_lshl_b32 s10, s45, 2
	v_lshl_add_u64 v[32:33], v[32:33], 0, s[10:11]
	global_store_dword v[32:33], v34, off
.LBB0_899:
	s_or_b64 exec, exec, s[0:1]
	s_waitcnt vmcnt(10)
	v_pk_add_f32 v[30:31], v[30:31], v[78:79]
	v_pk_add_f32 v[28:29], v[28:29], v[76:77]
	v_pk_add_f32 v[34:35], v[26:27], v[74:75]
	v_pk_add_f32 v[26:27], v[24:25], v[72:73]
	v_mul_f32_e32 v24, v29, v29
	v_mul_f32_e32 v25, v31, v31
	v_fmac_f32_e32 v24, v28, v28
	v_fmac_f32_e32 v25, v30, v30
	v_add_f32_e32 v24, v24, v25
	v_mul_f32_e32 v25, v27, v27
	v_mul_f32_e32 v36, v35, v35
	v_fmac_f32_e32 v25, v26, v26
	v_fmac_f32_e32 v36, v34, v34
	s_waitcnt lgkmcnt(0)
	v_lshlrev_b64 v[32:33], 10, v[112:113]
	v_add_f32_e32 v25, v25, v36
	v_lshl_add_u64 v[32:33], v[32:33], 0, v[180:181]
	v_add_f32_e32 v36, v24, v25
	v_cvt_pk_bf16_f32 v24, v28, v29
	v_cvt_pk_bf16_f32 v25, v30, v31
	s_waitcnt vmcnt(10)
	v_pk_add_f32 v[22:23], v[22:23], v[70:71]
	v_pk_add_f32 v[20:21], v[20:21], v[68:69]
	v_cvt_pk_bf16_f32 v26, v26, v27
	v_cvt_pk_bf16_f32 v27, v34, v35
	v_lshl_add_u64 v[28:29], v[32:33], 1, s[12:13]
	global_store_dwordx4 v[28:29], v[24:27], off sc1
	s_nop 1
	v_pk_add_f32 v[24:25], v[18:19], v[66:67]
	v_mul_f32_e32 v18, v21, v21
	v_mul_f32_e32 v19, v23, v23
	v_pk_add_f32 v[16:17], v[16:17], v[64:65]
	v_fmac_f32_e32 v18, v20, v20
	v_fmac_f32_e32 v19, v22, v22
	v_add_f32_e32 v18, v18, v19
	v_mul_f32_e32 v19, v17, v17
	v_mul_f32_e32 v26, v25, v25
	v_fmac_f32_e32 v19, v16, v16
	v_fmac_f32_e32 v26, v24, v24
	v_add_f32_e32 v19, v19, v26
	v_add_f32_e32 v18, v18, v19
	v_add_f32_e32 v26, v36, v18
	ds_bpermute_b32 v27, v197, v26
	v_cvt_pk_bf16_f32 v18, v20, v21
	v_cvt_pk_bf16_f32 v20, v16, v17
	v_cvt_pk_bf16_f32 v19, v22, v23
	v_cvt_pk_bf16_f32 v21, v24, v25
	s_waitcnt lgkmcnt(0)
	v_add_f32_e32 v16, v26, v27
	ds_bpermute_b32 v17, v198, v16
	v_lshl_add_u64 v[22:23], v[28:29], 0, s[14:15]
	global_store_dwordx4 v[22:23], v[18:21], off sc1
	s_nop 1
	s_and_saveexec_b64 s[0:1], s[6:7]
	s_cbranch_execz .LBB0_901
	s_waitcnt lgkmcnt(0)
	v_add_f32_e32 v18, v16, v17
	s_lshl_b32 s26, s51, 2
	v_lshlrev_b64 v[16:17], 6, v[112:113]
	s_ashr_i32 s27, s26, 31
	v_lshl_add_u64 v[16:17], s[18:19], 0, v[16:17]
	v_lshl_add_u64 v[16:17], s[26:27], 2, v[16:17]
	s_lshl_b32 s10, s45, 2
	v_lshl_add_u64 v[16:17], v[16:17], 0, s[10:11]
	global_store_dword v[16:17], v18, off
.LBB0_901:
	s_or_b64 exec, exec, s[0:1]
	s_waitcnt vmcnt(6)
	v_pk_add_f32 v[14:15], v[14:15], v[62:63]
	v_pk_add_f32 v[12:13], v[12:13], v[60:61]
	v_pk_add_f32 v[18:19], v[10:11], v[58:59]
	v_pk_add_f32 v[10:11], v[8:9], v[56:57]
	v_mul_f32_e32 v8, v13, v13
	v_mul_f32_e32 v9, v15, v15
	v_fmac_f32_e32 v8, v12, v12
	v_fmac_f32_e32 v9, v14, v14
	v_add_f32_e32 v8, v8, v9
	v_mul_f32_e32 v9, v11, v11
	v_mul_f32_e32 v20, v19, v19
	v_fmac_f32_e32 v9, v10, v10
	v_fmac_f32_e32 v20, v18, v18
	s_waitcnt lgkmcnt(0)
	v_lshlrev_b64 v[16:17], 10, v[96:97]
	v_add_f32_e32 v9, v9, v20
	v_lshl_add_u64 v[16:17], v[16:17], 0, v[180:181]
	v_add_f32_e32 v20, v8, v9
	v_cvt_pk_bf16_f32 v8, v12, v13
	v_cvt_pk_bf16_f32 v9, v14, v15
	s_waitcnt vmcnt(6)
	v_pk_add_f32 v[6:7], v[6:7], v[54:55]
	v_pk_add_f32 v[4:5], v[4:5], v[52:53]
	v_cvt_pk_bf16_f32 v10, v10, v11
	v_cvt_pk_bf16_f32 v11, v18, v19
	v_lshl_add_u64 v[12:13], v[16:17], 1, s[12:13]
	global_store_dwordx4 v[12:13], v[8:11], off sc1
	s_nop 1
	v_pk_add_f32 v[8:9], v[2:3], v[50:51]
	v_mul_f32_e32 v2, v5, v5
	v_mul_f32_e32 v3, v7, v7
	v_pk_add_f32 v[0:1], v[0:1], v[48:49]
	v_fmac_f32_e32 v2, v4, v4
	v_fmac_f32_e32 v3, v6, v6
	v_add_f32_e32 v2, v2, v3
	v_mul_f32_e32 v3, v1, v1
	v_mul_f32_e32 v10, v9, v9
	v_fmac_f32_e32 v3, v0, v0
	v_fmac_f32_e32 v10, v8, v8
	v_add_f32_e32 v3, v3, v10
	v_add_f32_e32 v2, v2, v3
	v_add_f32_e32 v10, v20, v2
	ds_bpermute_b32 v11, v197, v10
	v_cvt_pk_bf16_f32 v2, v4, v5
	v_cvt_pk_bf16_f32 v4, v0, v1
	v_cvt_pk_bf16_f32 v3, v6, v7
	v_cvt_pk_bf16_f32 v5, v8, v9
	s_waitcnt lgkmcnt(0)
	v_add_f32_e32 v0, v10, v11
	ds_bpermute_b32 v1, v198, v0
	v_lshl_add_u64 v[6:7], v[12:13], 0, s[14:15]
	global_store_dwordx4 v[6:7], v[2:5], off sc1
	s_nop 1
	s_and_saveexec_b64 s[0:1], s[6:7]
	s_cbranch_execz .LBB0_903
	s_waitcnt lgkmcnt(0)
	v_add_f32_e32 v2, v0, v1
	s_lshl_b32 s26, s51, 2
	v_lshlrev_b64 v[0:1], 6, v[96:97]
	s_ashr_i32 s27, s26, 31
	v_lshl_add_u64 v[0:1], s[18:19], 0, v[0:1]
	v_lshl_add_u64 v[0:1], s[26:27], 2, v[0:1]
	s_lshl_b32 s10, s45, 2
	v_lshl_add_u64 v[0:1], v[0:1], 0, s[10:11]
	global_store_dword v[0:1], v2, off

.LBB0_1097:
	v_lshl_add_u32 v202, s24, 8, v171
	v_lshl_or_b32 v128, s47, 8, v213
	v_ashrrev_i32_e32 v203, 31, v202
	v_lshlrev_b64 v[130:131], 11, v[202:203]
	v_ashrrev_i32_e32 v129, 31, v128
	v_lshl_add_u64 v[130:131], s[12:13], 0, v[130:131]
	v_lshlrev_b64 v[204:205], 1, v[128:129]
	v_lshl_add_u64 v[226:227], v[130:131], 0, v[204:205]
	global_load_dwordx4 v[218:221], v[226:227], off
	global_load_dwordx4 v[222:225], v[226:227], off offset:256
	v_or_b32_e32 v208, 16, v202
	v_or_b32_e32 v200, 32, v202
	v_or_b32_e32 v196, 48, v202
	v_add_u32_e32 v192, 0x80, v202
	v_add_u32_e32 v188, 0x90, v202
	v_ashrrev_i32_e32 v209, 31, v208
	v_ashrrev_i32_e32 v201, 31, v200
	v_ashrrev_i32_e32 v197, 31, v196
	v_ashrrev_i32_e32 v193, 31, v192
	v_ashrrev_i32_e32 v189, 31, v188
	v_lshlrev_b64 v[128:129], 11, v[208:209]
	v_lshlrev_b64 v[130:131], 11, v[200:201]
	v_lshlrev_b64 v[132:133], 11, v[196:197]
	v_lshlrev_b64 v[134:135], 11, v[192:193]
	v_lshlrev_b64 v[136:137], 11, v[188:189]
	v_lshl_add_u64 v[128:129], s[12:13], 0, v[128:129]
	v_lshl_add_u64 v[130:131], s[12:13], 0, v[130:131]
	v_lshl_add_u64 v[132:133], s[12:13], 0, v[132:133]
	v_lshl_add_u64 v[134:135], s[12:13], 0, v[134:135]
	v_lshl_add_u64 v[136:137], s[12:13], 0, v[136:137]
	v_lshl_add_u64 v[210:211], v[128:129], 0, v[204:205]
	v_lshl_add_u64 v[206:207], v[130:131], 0, v[204:205]
	v_lshl_add_u64 v[198:199], v[132:133], 0, v[204:205]
	v_lshl_add_u64 v[194:195], v[134:135], 0, v[204:205]
	v_lshl_add_u64 v[190:191], v[136:137], 0, v[204:205]
	global_load_dwordx4 v[164:167], v[210:211], off
	global_load_dwordx4 v[160:163], v[210:211], off offset:256
	global_load_dwordx4 v[156:159], v[206:207], off
	global_load_dwordx4 v[152:155], v[206:207], off offset:256
	global_load_dwordx4 v[148:151], v[198:199], off
	global_load_dwordx4 v[144:147], v[198:199], off offset:256
	global_load_dwordx4 v[140:143], v[194:195], off
	global_load_dwordx4 v[136:139], v[194:195], off offset:256
	global_load_dwordx4 v[132:135], v[190:191], off
	global_load_dwordx4 v[128:131], v[190:191], off offset:256
	v_lshl_add_u64 v[228:229], v[226:227], 0, s[14:15]
	s_waitcnt vmcnt(8)
	v_lshlrev_b32_e32 v230, 16, v218
	v_and_b32_e32 v231, 0xffff0000, v218
	v_lshlrev_b32_e32 v218, 16, v219
	v_and_b32_e32 v219, 0xffff0000, v219
	v_lshlrev_b32_e32 v232, 16, v220
	v_and_b32_e32 v233, 0xffff0000, v220
	v_lshlrev_b32_e32 v220, 16, v221
	v_and_b32_e32 v221, 0xffff0000, v221
	v_lshlrev_b32_e32 v234, 16, v222
	v_and_b32_e32 v235, 0xffff0000, v222
	v_lshlrev_b32_e32 v222, 16, v223
	v_and_b32_e32 v223, 0xffff0000, v223
	v_lshlrev_b32_e32 v236, 16, v224
	v_and_b32_e32 v237, 0xffff0000, v224
	v_lshlrev_b32_e32 v224, 16, v225
	v_and_b32_e32 v225, 0xffff0000, v225
	v_pk_add_f32 v[126:127], v[126:127], v[218:219]
	v_pk_add_f32 v[124:125], v[124:125], v[230:231]
	v_pk_add_f32 v[122:123], v[122:123], v[220:221]
	v_pk_add_f32 v[120:121], v[120:121], v[232:233]
	v_pk_add_f32 v[118:119], v[118:119], v[222:223]
	v_pk_add_f32 v[218:219], v[114:115], v[224:225]
	v_mul_f32_e32 v222, v125, v125
	v_mul_f32_e32 v223, v127, v127
	v_mul_f32_e32 v224, v121, v121
	v_mul_f32_e32 v225, v123, v123
	v_pk_add_f32 v[220:221], v[112:113], v[236:237]
	v_cvt_pk_bf16_f32 v112, v124, v125
	v_cvt_pk_bf16_f32 v113, v126, v127
	v_fmac_f32_e32 v222, v124, v124
	v_fmac_f32_e32 v223, v126, v126
	v_fmac_f32_e32 v224, v120, v120
	v_fmac_f32_e32 v225, v122, v122
	v_pk_add_f32 v[116:117], v[116:117], v[234:235]
	v_cvt_pk_bf16_f32 v114, v120, v121
	v_cvt_pk_bf16_f32 v115, v122, v123
	global_store_dwordx4 v[226:227], v[112:115], off sc1
	s_nop 1
	v_add_f32_e32 v112, v222, v223
	v_add_f32_e32 v113, v224, v225
	v_mul_f32_e32 v121, v117, v117
	v_mul_f32_e32 v123, v119, v119
	v_add_f32_e32 v112, v112, v113
	v_mul_f32_e32 v113, v221, v221
	v_mul_f32_e32 v115, v219, v219
	v_fmac_f32_e32 v121, v116, v116
	v_fmac_f32_e32 v123, v118, v118
	v_fmac_f32_e32 v113, v220, v220
	v_fmac_f32_e32 v115, v218, v218
	v_add_f32_e32 v114, v121, v123
	v_add_f32_e32 v113, v113, v115
	v_add_f32_e32 v113, v114, v113
	v_and_b32_e32 v114, 64, v217
	v_add_f32_e32 v112, v112, v113
	v_xor_b32_e32 v113, 16, v217
	v_add_u32_e32 v121, 64, v114
	v_cmp_lt_i32_e32 vcc, v113, v121
	v_cvt_pk_bf16_f32 v114, v116, v117
	v_cvt_pk_bf16_f32 v115, v118, v119
	v_cndmask_b32_e32 v113, v217, v113, vcc
	v_lshlrev_b32_e32 v120, 2, v113
	ds_bpermute_b32 v113, v120, v112
	v_cvt_pk_bf16_f32 v116, v220, v221
	v_cvt_pk_bf16_f32 v117, v218, v219
	global_store_dwordx4 v[228:229], v[114:117], off sc1
	s_nop 1
	s_waitcnt lgkmcnt(0)
	v_add_f32_e32 v112, v112, v113
	v_xor_b32_e32 v113, 32, v217
	v_cmp_lt_i32_e32 vcc, v113, v121
	s_nop 1
	v_cndmask_b32_e32 v113, v217, v113, vcc
	v_lshlrev_b32_e32 v121, 2, v113
	ds_bpermute_b32 v113, v121, v112
	s_and_saveexec_b64 s[0:1], s[6:7]
	s_cbranch_execz .LBB0_1099
	s_waitcnt lgkmcnt(0)
	v_add_f32_e32 v114, v112, v113
	s_lshl_b32 s24, s47, 2
	v_lshlrev_b64 v[112:113], 6, v[202:203]
	s_ashr_i32 s25, s24, 31
	v_lshl_add_u64 v[112:113], s[16:17], 0, v[112:113]
	v_lshl_add_u64 v[112:113], s[24:25], 2, v[112:113]
	s_lshl_b32 s4, s41, 2
	v_lshl_add_u64 v[112:113], v[112:113], 0, s[4:5]
	global_store_dword v[112:113], v114, off

.LBB0_1101:
	s_or_b64 exec, exec, s[0:1]
	v_add_u32_e32 v116, 0xa0, v202
	v_ashrrev_i32_e32 v117, 31, v116
	s_waitcnt lgkmcnt(0)
	v_lshlrev_b64 v[96:97], 11, v[116:117]
	v_add_u32_e32 v112, 0xb0, v202
	v_lshl_add_u64 v[96:97], s[12:13], 0, v[96:97]
	v_ashrrev_i32_e32 v113, 31, v112
	v_lshl_add_u64 v[118:119], v[96:97], 0, v[204:205]
	v_lshlrev_b64 v[96:97], 11, v[112:113]
	v_lshl_add_u64 v[96:97], s[12:13], 0, v[96:97]
	v_lshl_add_u64 v[114:115], v[96:97], 0, v[204:205]
	global_load_dwordx4 v[108:111], v[118:119], off
	global_load_dwordx4 v[104:107], v[118:119], off offset:256
	global_load_dwordx4 v[100:103], v[114:115], off
	global_load_dwordx4 v[96:99], v[114:115], off offset:256
	s_waitcnt vmcnt(14)
	v_lshlrev_b32_e32 v124, 16, v156
	v_and_b32_e32 v125, 0xffff0000, v156
	v_lshlrev_b32_e32 v126, 16, v157
	v_and_b32_e32 v127, 0xffff0000, v157
	v_lshlrev_b32_e32 v156, 16, v158
	v_and_b32_e32 v157, 0xffff0000, v158
	v_lshlrev_b32_e32 v158, 16, v159
	v_and_b32_e32 v159, 0xffff0000, v159
	v_pk_add_f32 v[94:95], v[94:95], v[126:127]
	v_pk_add_f32 v[92:93], v[92:93], v[124:125]
	v_pk_add_f32 v[124:125], v[90:91], v[158:159]
	v_pk_add_f32 v[90:91], v[88:89], v[156:157]
	v_mul_f32_e32 v88, v93, v93
	v_mul_f32_e32 v89, v95, v95
	v_fmac_f32_e32 v88, v92, v92
	v_fmac_f32_e32 v89, v94, v94
	v_add_f32_e32 v88, v88, v89
	v_mul_f32_e32 v89, v91, v91
	v_mul_f32_e32 v126, v125, v125
	v_fmac_f32_e32 v89, v90, v90
	v_fmac_f32_e32 v126, v124, v124
	v_lshlrev_b32_e32 v160, 16, v152
	v_and_b32_e32 v161, 0xffff0000, v152
	v_lshlrev_b32_e32 v152, 16, v153
	v_and_b32_e32 v153, 0xffff0000, v153
	v_add_f32_e32 v89, v89, v126
	v_lshlrev_b32_e32 v162, 16, v154
	v_and_b32_e32 v163, 0xffff0000, v154
	v_lshlrev_b32_e32 v154, 16, v155
	v_and_b32_e32 v155, 0xffff0000, v155
	v_add_f32_e32 v126, v88, v89
	v_cvt_pk_bf16_f32 v88, v92, v93
	v_cvt_pk_bf16_f32 v89, v94, v95
	v_pk_add_f32 v[86:87], v[86:87], v[152:153]
	v_pk_add_f32 v[84:85], v[84:85], v[160:161]
	v_cvt_pk_bf16_f32 v90, v90, v91
	v_cvt_pk_bf16_f32 v91, v124, v125
	global_store_dwordx4 v[206:207], v[88:91], off sc1
	s_nop 1
	v_pk_add_f32 v[88:89], v[82:83], v[154:155]
	v_mul_f32_e32 v82, v85, v85
	v_mul_f32_e32 v83, v87, v87
	v_pk_add_f32 v[80:81], v[80:81], v[162:163]
	v_fmac_f32_e32 v82, v84, v84
	v_fmac_f32_e32 v83, v86, v86
	v_add_f32_e32 v82, v82, v83
	v_mul_f32_e32 v83, v81, v81
	v_mul_f32_e32 v90, v89, v89
	v_fmac_f32_e32 v83, v80, v80
	v_fmac_f32_e32 v90, v88, v88
	v_add_f32_e32 v83, v83, v90
	v_add_f32_e32 v82, v82, v83
	v_add_f32_e32 v90, v126, v82
	ds_bpermute_b32 v91, v120, v90
	v_cvt_pk_bf16_f32 v82, v84, v85
	v_cvt_pk_bf16_f32 v84, v80, v81
	v_lshl_add_u64 v[122:123], v[206:207], 0, s[14:15]
	v_cvt_pk_bf16_f32 v83, v86, v87
	s_waitcnt lgkmcnt(0)
	v_add_f32_e32 v80, v90, v91
	ds_bpermute_b32 v81, v121, v80
	v_cvt_pk_bf16_f32 v85, v88, v89
	global_store_dwordx4 v[122:123], v[82:85], off sc1
	s_nop 1
	s_and_saveexec_b64 s[0:1], s[6:7]
	s_cbranch_execz .LBB0_1103
	s_waitcnt lgkmcnt(0)
	v_add_f32_e32 v82, v80, v81
	s_lshl_b32 s24, s47, 2
	v_lshlrev_b64 v[80:81], 6, v[200:201]
	s_ashr_i32 s25, s24, 31
	v_lshl_add_u64 v[80:81], s[16:17], 0, v[80:81]
	v_lshl_add_u64 v[80:81], s[24:25], 2, v[80:81]
	s_lshl_b32 s4, s41, 2
	v_lshl_add_u64 v[80:81], v[80:81], 0, s[4:5]
	global_store_dword v[80:81], v82, off

.LBB0_1105:
	s_or_b64 exec, exec, s[0:1]
	s_waitcnt vmcnt(16)
	v_lshlrev_b32_e32 v66, 16, v140
	v_and_b32_e32 v67, 0xffff0000, v140
	v_lshlrev_b32_e32 v68, 16, v141
	v_and_b32_e32 v69, 0xffff0000, v141
	v_lshlrev_b32_e32 v70, 16, v142
	v_and_b32_e32 v71, 0xffff0000, v142
	v_lshlrev_b32_e32 v72, 16, v143
	v_and_b32_e32 v73, 0xffff0000, v143
	v_pk_add_f32 v[62:63], v[62:63], v[68:69]
	v_pk_add_f32 v[60:61], v[60:61], v[66:67]
	v_pk_add_f32 v[66:67], v[58:59], v[72:73]
	v_pk_add_f32 v[58:59], v[56:57], v[70:71]
	v_mul_f32_e32 v56, v61, v61
	v_mul_f32_e32 v57, v63, v63
	v_fmac_f32_e32 v56, v60, v60
	v_fmac_f32_e32 v57, v62, v62
	v_add_f32_e32 v56, v56, v57
	v_mul_f32_e32 v57, v59, v59
	v_mul_f32_e32 v68, v67, v67
	v_fmac_f32_e32 v57, v58, v58
	v_fmac_f32_e32 v68, v66, v66
	v_lshlrev_b32_e32 v74, 16, v136
	v_and_b32_e32 v75, 0xffff0000, v136
	v_lshlrev_b32_e32 v76, 16, v137
	v_and_b32_e32 v77, 0xffff0000, v137
	v_add_f32_e32 v57, v57, v68
	v_lshlrev_b32_e32 v80, 16, v139
	v_and_b32_e32 v81, 0xffff0000, v139
	v_add_f32_e32 v68, v56, v57
	v_cvt_pk_bf16_f32 v56, v60, v61
	v_cvt_pk_bf16_f32 v57, v62, v63
	v_pk_add_f32 v[54:55], v[54:55], v[76:77]
	v_pk_add_f32 v[52:53], v[52:53], v[74:75]
	v_lshlrev_b32_e32 v78, 16, v138
	v_and_b32_e32 v79, 0xffff0000, v138
	v_cvt_pk_bf16_f32 v58, v58, v59
	v_cvt_pk_bf16_f32 v59, v66, v67
	global_store_dwordx4 v[194:195], v[56:59], off sc1
	s_nop 1
	v_pk_add_f32 v[56:57], v[50:51], v[80:81]
	v_mul_f32_e32 v50, v53, v53
	v_mul_f32_e32 v51, v55, v55
	v_pk_add_f32 v[48:49], v[48:49], v[78:79]
	v_fmac_f32_e32 v50, v52, v52
	v_fmac_f32_e32 v51, v54, v54
	v_add_f32_e32 v50, v50, v51
	v_mul_f32_e32 v51, v49, v49
	v_mul_f32_e32 v58, v57, v57
	v_fmac_f32_e32 v51, v48, v48
	v_fmac_f32_e32 v58, v56, v56
	v_add_f32_e32 v51, v51, v58
	v_add_f32_e32 v50, v50, v51
	v_add_f32_e32 v58, v68, v50
	ds_bpermute_b32 v59, v120, v58
	v_cvt_pk_bf16_f32 v50, v52, v53
	v_cvt_pk_bf16_f32 v52, v48, v49
	s_waitcnt lgkmcnt(1)
	v_lshl_add_u64 v[64:65], v[194:195], 0, s[14:15]
	v_cvt_pk_bf16_f32 v51, v54, v55
	s_waitcnt lgkmcnt(0)
	v_add_f32_e32 v48, v58, v59
	ds_bpermute_b32 v49, v121, v48
	v_cvt_pk_bf16_f32 v53, v56, v57
	global_store_dwordx4 v[64:65], v[50:53], off sc1
	s_nop 1
	s_and_saveexec_b64 s[0:1], s[6:7]
	s_cbranch_execz .LBB0_1107
	s_waitcnt lgkmcnt(0)
	v_add_f32_e32 v50, v48, v49
	s_lshl_b32 s24, s47, 2
	v_lshlrev_b64 v[48:49], 6, v[192:193]
	s_ashr_i32 s25, s24, 31
	v_lshl_add_u64 v[48:49], s[16:17], 0, v[48:49]
	v_lshl_add_u64 v[48:49], s[24:25], 2, v[48:49]
	s_lshl_b32 s4, s41, 2
	v_lshl_add_u64 v[48:49], v[48:49], 0, s[4:5]
	global_store_dword v[48:49], v50, off

.LBB0_1109:
	s_or_b64 exec, exec, s[0:1]
	s_waitcnt vmcnt(14)
	v_lshlrev_b32_e32 v34, 16, v108
	v_and_b32_e32 v35, 0xffff0000, v108
	v_lshlrev_b32_e32 v36, 16, v109
	v_and_b32_e32 v37, 0xffff0000, v109
	v_lshlrev_b32_e32 v38, 16, v110
	v_and_b32_e32 v39, 0xffff0000, v110
	v_lshlrev_b32_e32 v40, 16, v111
	v_and_b32_e32 v41, 0xffff0000, v111
	v_pk_add_f32 v[30:31], v[30:31], v[36:37]
	v_pk_add_f32 v[28:29], v[28:29], v[34:35]
	v_pk_add_f32 v[34:35], v[26:27], v[40:41]
	v_pk_add_f32 v[26:27], v[24:25], v[38:39]
	v_mul_f32_e32 v24, v29, v29
	v_mul_f32_e32 v25, v31, v31
	v_fmac_f32_e32 v24, v28, v28
	v_fmac_f32_e32 v25, v30, v30
	v_add_f32_e32 v24, v24, v25
	v_mul_f32_e32 v25, v27, v27
	v_mul_f32_e32 v36, v35, v35
	v_fmac_f32_e32 v25, v26, v26
	v_fmac_f32_e32 v36, v34, v34
	s_waitcnt vmcnt(14)
	v_lshlrev_b32_e32 v42, 16, v104
	v_and_b32_e32 v43, 0xffff0000, v104
	v_lshlrev_b32_e32 v44, 16, v105
	v_and_b32_e32 v45, 0xffff0000, v105
	v_add_f32_e32 v25, v25, v36
	v_lshlrev_b32_e32 v48, 16, v107
	v_and_b32_e32 v49, 0xffff0000, v107
	v_add_f32_e32 v36, v24, v25
	v_cvt_pk_bf16_f32 v24, v28, v29
	v_cvt_pk_bf16_f32 v25, v30, v31
	v_pk_add_f32 v[22:23], v[22:23], v[44:45]
	v_pk_add_f32 v[20:21], v[20:21], v[42:43]
	v_lshlrev_b32_e32 v46, 16, v106
	v_and_b32_e32 v47, 0xffff0000, v106
	v_cvt_pk_bf16_f32 v26, v26, v27
	v_cvt_pk_bf16_f32 v27, v34, v35
	global_store_dwordx4 v[118:119], v[24:27], off sc1
	s_nop 1
	v_pk_add_f32 v[24:25], v[18:19], v[48:49]
	v_mul_f32_e32 v18, v21, v21
	v_mul_f32_e32 v19, v23, v23
	v_pk_add_f32 v[16:17], v[16:17], v[46:47]
	v_fmac_f32_e32 v18, v20, v20
	v_fmac_f32_e32 v19, v22, v22
	v_add_f32_e32 v18, v18, v19
	v_mul_f32_e32 v19, v17, v17
	v_mul_f32_e32 v26, v25, v25
	v_fmac_f32_e32 v19, v16, v16
	v_fmac_f32_e32 v26, v24, v24
	v_add_f32_e32 v19, v19, v26
	v_add_f32_e32 v18, v18, v19
	v_add_f32_e32 v26, v36, v18
	ds_bpermute_b32 v27, v120, v26
	v_cvt_pk_bf16_f32 v18, v20, v21
	v_cvt_pk_bf16_f32 v20, v16, v17
	s_waitcnt lgkmcnt(1)
	v_lshl_add_u64 v[32:33], v[118:119], 0, s[14:15]
	v_cvt_pk_bf16_f32 v19, v22, v23
	s_waitcnt lgkmcnt(0)
	v_add_f32_e32 v16, v26, v27
	ds_bpermute_b32 v17, v121, v16
	v_cvt_pk_bf16_f32 v21, v24, v25
	global_store_dwordx4 v[32:33], v[18:21], off sc1
	s_nop 1
	s_and_saveexec_b64 s[0:1], s[6:7]
	s_cbranch_execz .LBB0_1111
	s_waitcnt lgkmcnt(0)
	v_add_f32_e32 v18, v16, v17
	s_lshl_b32 s24, s47, 2
	v_lshlrev_b64 v[16:17], 6, v[116:117]
	s_ashr_i32 s25, s24, 31
	v_lshl_add_u64 v[16:17], s[16:17], 0, v[16:17]
	v_lshl_add_u64 v[16:17], s[24:25], 2, v[16:17]
	s_lshl_b32 s4, s41, 2
	v_lshl_add_u64 v[16:17], v[16:17], 0, s[4:5]
	global_store_dword v[16:17], v18, off
.LBB0_1111:
	s_or_b64 exec, exec, s[0:1]
	s_waitcnt vmcnt(15)
	v_lshlrev_b32_e32 v18, 16, v100
	v_and_b32_e32 v19, 0xffff0000, v100
	v_lshlrev_b32_e32 v20, 16, v101
	v_and_b32_e32 v21, 0xffff0000, v101
	v_lshlrev_b32_e32 v22, 16, v102
	v_and_b32_e32 v23, 0xffff0000, v102
	v_lshlrev_b32_e32 v24, 16, v103
	v_and_b32_e32 v25, 0xffff0000, v103
	v_pk_add_f32 v[14:15], v[14:15], v[20:21]
	v_pk_add_f32 v[12:13], v[12:13], v[18:19]
	v_pk_add_f32 v[18:19], v[10:11], v[24:25]
	v_pk_add_f32 v[10:11], v[8:9], v[22:23]
	v_mul_f32_e32 v8, v13, v13
	v_mul_f32_e32 v9, v15, v15
	v_fmac_f32_e32 v8, v12, v12
	v_fmac_f32_e32 v9, v14, v14
	v_add_f32_e32 v8, v8, v9
	v_mul_f32_e32 v9, v11, v11
	v_mul_f32_e32 v20, v19, v19
	v_fmac_f32_e32 v9, v10, v10
	v_fmac_f32_e32 v20, v18, v18
	s_waitcnt vmcnt(15)
	v_lshlrev_b32_e32 v26, 16, v96
	v_and_b32_e32 v27, 0xffff0000, v96
	v_lshlrev_b32_e32 v28, 16, v97
	v_and_b32_e32 v29, 0xffff0000, v97
	v_add_f32_e32 v9, v9, v20
	v_lshlrev_b32_e32 v32, 16, v99
	v_and_b32_e32 v33, 0xffff0000, v99
	v_add_f32_e32 v20, v8, v9
	v_cvt_pk_bf16_f32 v8, v12, v13
	v_cvt_pk_bf16_f32 v9, v14, v15
	v_pk_add_f32 v[6:7], v[6:7], v[28:29]
	v_pk_add_f32 v[4:5], v[4:5], v[26:27]
	v_lshlrev_b32_e32 v30, 16, v98
	v_and_b32_e32 v31, 0xffff0000, v98
	v_cvt_pk_bf16_f32 v10, v10, v11
	v_cvt_pk_bf16_f32 v11, v18, v19
	global_store_dwordx4 v[114:115], v[8:11], off sc1
	s_nop 1
	v_pk_add_f32 v[8:9], v[2:3], v[32:33]
	v_mul_f32_e32 v2, v5, v5
	v_mul_f32_e32 v3, v7, v7
	v_pk_add_f32 v[0:1], v[0:1], v[30:31]
	v_fmac_f32_e32 v2, v4, v4
	v_fmac_f32_e32 v3, v6, v6
	v_add_f32_e32 v2, v2, v3
	v_mul_f32_e32 v3, v1, v1
	v_mul_f32_e32 v10, v9, v9
	v_fmac_f32_e32 v3, v0, v0
	v_fmac_f32_e32 v10, v8, v8
	v_add_f32_e32 v3, v3, v10
	v_add_f32_e32 v2, v2, v3
	v_add_f32_e32 v10, v20, v2
	ds_bpermute_b32 v11, v120, v10
	v_cvt_pk_bf16_f32 v2, v4, v5
	v_cvt_pk_bf16_f32 v4, v0, v1
	s_waitcnt lgkmcnt(1)
	v_lshl_add_u64 v[16:17], v[114:115], 0, s[14:15]
	v_cvt_pk_bf16_f32 v3, v6, v7
	s_waitcnt lgkmcnt(0)
	v_add_f32_e32 v0, v10, v11
	ds_bpermute_b32 v1, v121, v0
	v_cvt_pk_bf16_f32 v5, v8, v9
	global_store_dwordx4 v[16:17], v[2:5], off sc1
	s_nop 1
	s_and_saveexec_b64 s[0:1], s[6:7]
	s_cbranch_execz .LBB0_1113
	s_waitcnt lgkmcnt(0)
	v_add_f32_e32 v2, v0, v1
	s_lshl_b32 s24, s47, 2
	v_lshlrev_b64 v[0:1], 6, v[112:113]
	s_ashr_i32 s25, s24, 31
	v_lshl_add_u64 v[0:1], s[16:17], 0, v[0:1]
	v_lshl_add_u64 v[0:1], s[24:25], 2, v[0:1]
	s_lshl_b32 s4, s41, 2
	v_lshl_add_u64 v[0:1], v[0:1], 0, s[4:5]
	global_store_dword v[0:1], v2, off

.LBB0_2667:
	v_lshl_add_u32 v202, s24, 8, v171
	v_lshl_or_b32 v128, s45, 8, v213
	v_ashrrev_i32_e32 v203, 31, v202
	v_lshlrev_b64 v[130:131], 11, v[202:203]
	v_ashrrev_i32_e32 v129, 31, v128
	v_lshl_add_u64 v[130:131], s[12:13], 0, v[130:131]
	v_lshlrev_b64 v[204:205], 1, v[128:129]
	v_lshl_add_u64 v[226:227], v[130:131], 0, v[204:205]
	global_load_dwordx4 v[218:221], v[226:227], off
	global_load_dwordx4 v[222:225], v[226:227], off offset:256
	v_or_b32_e32 v208, 16, v202
	v_or_b32_e32 v200, 32, v202
	v_or_b32_e32 v196, 48, v202
	v_add_u32_e32 v192, 0x80, v202
	v_add_u32_e32 v188, 0x90, v202
	v_ashrrev_i32_e32 v209, 31, v208
	v_ashrrev_i32_e32 v201, 31, v200
	v_ashrrev_i32_e32 v197, 31, v196
	v_ashrrev_i32_e32 v193, 31, v192
	v_ashrrev_i32_e32 v189, 31, v188
	v_lshlrev_b64 v[128:129], 11, v[208:209]
	v_lshlrev_b64 v[130:131], 11, v[200:201]
	v_lshlrev_b64 v[132:133], 11, v[196:197]
	v_lshlrev_b64 v[134:135], 11, v[192:193]
	v_lshlrev_b64 v[136:137], 11, v[188:189]
	v_lshl_add_u64 v[128:129], s[12:13], 0, v[128:129]
	v_lshl_add_u64 v[130:131], s[12:13], 0, v[130:131]
	v_lshl_add_u64 v[132:133], s[12:13], 0, v[132:133]
	v_lshl_add_u64 v[134:135], s[12:13], 0, v[134:135]
	v_lshl_add_u64 v[136:137], s[12:13], 0, v[136:137]
	v_lshl_add_u64 v[210:211], v[128:129], 0, v[204:205]
	v_lshl_add_u64 v[206:207], v[130:131], 0, v[204:205]
	v_lshl_add_u64 v[198:199], v[132:133], 0, v[204:205]
	v_lshl_add_u64 v[194:195], v[134:135], 0, v[204:205]
	v_lshl_add_u64 v[190:191], v[136:137], 0, v[204:205]
	global_load_dwordx4 v[164:167], v[210:211], off
	global_load_dwordx4 v[160:163], v[210:211], off offset:256
	global_load_dwordx4 v[156:159], v[206:207], off
	global_load_dwordx4 v[152:155], v[206:207], off offset:256
	global_load_dwordx4 v[148:151], v[198:199], off
	global_load_dwordx4 v[144:147], v[198:199], off offset:256
	global_load_dwordx4 v[140:143], v[194:195], off
	global_load_dwordx4 v[136:139], v[194:195], off offset:256
	global_load_dwordx4 v[132:135], v[190:191], off
	global_load_dwordx4 v[128:131], v[190:191], off offset:256
	v_lshl_add_u64 v[228:229], v[226:227], 0, s[14:15]
	s_waitcnt vmcnt(8)
	v_lshlrev_b32_e32 v230, 16, v218
	v_and_b32_e32 v231, 0xffff0000, v218
	v_lshlrev_b32_e32 v218, 16, v219
	v_and_b32_e32 v219, 0xffff0000, v219
	v_lshlrev_b32_e32 v232, 16, v220
	v_and_b32_e32 v233, 0xffff0000, v220
	v_lshlrev_b32_e32 v220, 16, v221
	v_and_b32_e32 v221, 0xffff0000, v221
	v_lshlrev_b32_e32 v234, 16, v222
	v_and_b32_e32 v235, 0xffff0000, v222
	v_lshlrev_b32_e32 v222, 16, v223
	v_and_b32_e32 v223, 0xffff0000, v223
	v_lshlrev_b32_e32 v236, 16, v224
	v_and_b32_e32 v237, 0xffff0000, v224
	v_lshlrev_b32_e32 v224, 16, v225
	v_and_b32_e32 v225, 0xffff0000, v225
	v_pk_add_f32 v[126:127], v[126:127], v[218:219]
	v_pk_add_f32 v[124:125], v[124:125], v[230:231]
	v_pk_add_f32 v[122:123], v[122:123], v[220:221]
	v_pk_add_f32 v[120:121], v[120:121], v[232:233]
	v_pk_add_f32 v[118:119], v[118:119], v[222:223]
	v_pk_add_f32 v[218:219], v[114:115], v[224:225]
	v_mul_f32_e32 v222, v125, v125
	v_mul_f32_e32 v223, v127, v127
	v_mul_f32_e32 v224, v121, v121
	v_mul_f32_e32 v225, v123, v123
	v_pk_add_f32 v[220:221], v[112:113], v[236:237]
	v_cvt_pk_bf16_f32 v112, v124, v125
	v_cvt_pk_bf16_f32 v113, v126, v127
	v_fmac_f32_e32 v222, v124, v124
	v_fmac_f32_e32 v223, v126, v126
	v_fmac_f32_e32 v224, v120, v120
	v_fmac_f32_e32 v225, v122, v122
	v_pk_add_f32 v[116:117], v[116:117], v[234:235]
	v_cvt_pk_bf16_f32 v114, v120, v121
	v_cvt_pk_bf16_f32 v115, v122, v123
	global_store_dwordx4 v[226:227], v[112:115], off sc1
	s_nop 1
	v_add_f32_e32 v112, v222, v223
	v_add_f32_e32 v113, v224, v225
	v_mul_f32_e32 v121, v117, v117
	v_mul_f32_e32 v123, v119, v119
	v_add_f32_e32 v112, v112, v113
	v_mul_f32_e32 v113, v221, v221
	v_mul_f32_e32 v115, v219, v219
	v_fmac_f32_e32 v121, v116, v116
	v_fmac_f32_e32 v123, v118, v118
	v_fmac_f32_e32 v113, v220, v220
	v_fmac_f32_e32 v115, v218, v218
	v_add_f32_e32 v114, v121, v123
	v_add_f32_e32 v113, v113, v115
	v_add_f32_e32 v113, v114, v113
	v_and_b32_e32 v114, 64, v217
	v_add_f32_e32 v112, v112, v113
	v_xor_b32_e32 v113, 16, v217
	v_add_u32_e32 v121, 64, v114
	v_cmp_lt_i32_e32 vcc, v113, v121
	v_cvt_pk_bf16_f32 v114, v116, v117
	v_cvt_pk_bf16_f32 v115, v118, v119
	v_cndmask_b32_e32 v113, v217, v113, vcc
	v_lshlrev_b32_e32 v120, 2, v113
	ds_bpermute_b32 v113, v120, v112
	v_cvt_pk_bf16_f32 v116, v220, v221
	v_cvt_pk_bf16_f32 v117, v218, v219
	global_store_dwordx4 v[228:229], v[114:117], off sc1
	s_nop 1
	s_waitcnt lgkmcnt(0)
	v_add_f32_e32 v112, v112, v113
	v_xor_b32_e32 v113, 32, v217
	v_cmp_lt_i32_e32 vcc, v113, v121
	s_nop 1
	v_cndmask_b32_e32 v113, v217, v113, vcc
	v_lshlrev_b32_e32 v121, 2, v113
	ds_bpermute_b32 v113, v121, v112
	s_and_saveexec_b64 s[0:1], s[6:7]
	s_cbranch_execz .LBB0_2669
	s_waitcnt lgkmcnt(0)
	v_add_f32_e32 v114, v112, v113
	s_lshl_b32 s24, s45, 2
	v_lshlrev_b64 v[112:113], 6, v[202:203]
	s_ashr_i32 s25, s24, 31
	v_lshl_add_u64 v[112:113], s[16:17], 0, v[112:113]
	v_lshl_add_u64 v[112:113], s[24:25], 2, v[112:113]
	s_lshl_b32 s4, s40, 2
	v_lshl_add_u64 v[112:113], v[112:113], 0, s[4:5]
	global_store_dword v[112:113], v114, off

.LBB0_2671:
	s_or_b64 exec, exec, s[0:1]
	v_add_u32_e32 v116, 0xa0, v202
	v_ashrrev_i32_e32 v117, 31, v116
	s_waitcnt lgkmcnt(0)
	v_lshlrev_b64 v[96:97], 11, v[116:117]
	v_add_u32_e32 v112, 0xb0, v202
	v_lshl_add_u64 v[96:97], s[12:13], 0, v[96:97]
	v_ashrrev_i32_e32 v113, 31, v112
	v_lshl_add_u64 v[118:119], v[96:97], 0, v[204:205]
	v_lshlrev_b64 v[96:97], 11, v[112:113]
	v_lshl_add_u64 v[96:97], s[12:13], 0, v[96:97]
	v_lshl_add_u64 v[114:115], v[96:97], 0, v[204:205]
	global_load_dwordx4 v[108:111], v[118:119], off
	global_load_dwordx4 v[104:107], v[118:119], off offset:256
	global_load_dwordx4 v[100:103], v[114:115], off
	global_load_dwordx4 v[96:99], v[114:115], off offset:256
	s_waitcnt vmcnt(14)
	v_lshlrev_b32_e32 v124, 16, v156
	v_and_b32_e32 v125, 0xffff0000, v156
	v_lshlrev_b32_e32 v126, 16, v157
	v_and_b32_e32 v127, 0xffff0000, v157
	v_lshlrev_b32_e32 v156, 16, v158
	v_and_b32_e32 v157, 0xffff0000, v158
	v_lshlrev_b32_e32 v158, 16, v159
	v_and_b32_e32 v159, 0xffff0000, v159
	v_pk_add_f32 v[94:95], v[94:95], v[126:127]
	v_pk_add_f32 v[92:93], v[92:93], v[124:125]
	v_pk_add_f32 v[124:125], v[90:91], v[158:159]
	v_pk_add_f32 v[90:91], v[88:89], v[156:157]
	v_mul_f32_e32 v88, v93, v93
	v_mul_f32_e32 v89, v95, v95
	v_fmac_f32_e32 v88, v92, v92
	v_fmac_f32_e32 v89, v94, v94
	v_add_f32_e32 v88, v88, v89
	v_mul_f32_e32 v89, v91, v91
	v_mul_f32_e32 v126, v125, v125
	v_fmac_f32_e32 v89, v90, v90
	v_fmac_f32_e32 v126, v124, v124
	v_lshlrev_b32_e32 v160, 16, v152
	v_and_b32_e32 v161, 0xffff0000, v152
	v_lshlrev_b32_e32 v152, 16, v153
	v_and_b32_e32 v153, 0xffff0000, v153
	v_add_f32_e32 v89, v89, v126
	v_lshlrev_b32_e32 v162, 16, v154
	v_and_b32_e32 v163, 0xffff0000, v154
	v_lshlrev_b32_e32 v154, 16, v155
	v_and_b32_e32 v155, 0xffff0000, v155
	v_add_f32_e32 v126, v88, v89
	v_cvt_pk_bf16_f32 v88, v92, v93
	v_cvt_pk_bf16_f32 v89, v94, v95
	v_pk_add_f32 v[86:87], v[86:87], v[152:153]
	v_pk_add_f32 v[84:85], v[84:85], v[160:161]
	v_cvt_pk_bf16_f32 v90, v90, v91
	v_cvt_pk_bf16_f32 v91, v124, v125
	global_store_dwordx4 v[206:207], v[88:91], off sc1
	s_nop 1
	v_pk_add_f32 v[88:89], v[82:83], v[154:155]
	v_mul_f32_e32 v82, v85, v85
	v_mul_f32_e32 v83, v87, v87
	v_pk_add_f32 v[80:81], v[80:81], v[162:163]
	v_fmac_f32_e32 v82, v84, v84
	v_fmac_f32_e32 v83, v86, v86
	v_add_f32_e32 v82, v82, v83
	v_mul_f32_e32 v83, v81, v81
	v_mul_f32_e32 v90, v89, v89
	v_fmac_f32_e32 v83, v80, v80
	v_fmac_f32_e32 v90, v88, v88
	v_add_f32_e32 v83, v83, v90
	v_add_f32_e32 v82, v82, v83
	v_add_f32_e32 v90, v126, v82
	ds_bpermute_b32 v91, v120, v90
	v_cvt_pk_bf16_f32 v82, v84, v85
	v_cvt_pk_bf16_f32 v84, v80, v81
	v_lshl_add_u64 v[122:123], v[206:207], 0, s[14:15]
	v_cvt_pk_bf16_f32 v83, v86, v87
	s_waitcnt lgkmcnt(0)
	v_add_f32_e32 v80, v90, v91
	ds_bpermute_b32 v81, v121, v80
	v_cvt_pk_bf16_f32 v85, v88, v89
	global_store_dwordx4 v[122:123], v[82:85], off sc1
	s_nop 1
	s_and_saveexec_b64 s[0:1], s[6:7]
	s_cbranch_execz .LBB0_2673
	s_waitcnt lgkmcnt(0)
	v_add_f32_e32 v82, v80, v81
	s_lshl_b32 s24, s45, 2
	v_lshlrev_b64 v[80:81], 6, v[200:201]
	s_ashr_i32 s25, s24, 31
	v_lshl_add_u64 v[80:81], s[16:17], 0, v[80:81]
	v_lshl_add_u64 v[80:81], s[24:25], 2, v[80:81]
	s_lshl_b32 s4, s40, 2
	v_lshl_add_u64 v[80:81], v[80:81], 0, s[4:5]
	global_store_dword v[80:81], v82, off

.LBB0_2675:
	s_or_b64 exec, exec, s[0:1]
	s_waitcnt vmcnt(16)
	v_lshlrev_b32_e32 v66, 16, v140
	v_and_b32_e32 v67, 0xffff0000, v140
	v_lshlrev_b32_e32 v68, 16, v141
	v_and_b32_e32 v69, 0xffff0000, v141
	v_lshlrev_b32_e32 v70, 16, v142
	v_and_b32_e32 v71, 0xffff0000, v142
	v_lshlrev_b32_e32 v72, 16, v143
	v_and_b32_e32 v73, 0xffff0000, v143
	v_pk_add_f32 v[62:63], v[62:63], v[68:69]
	v_pk_add_f32 v[60:61], v[60:61], v[66:67]
	v_pk_add_f32 v[66:67], v[58:59], v[72:73]
	v_pk_add_f32 v[58:59], v[56:57], v[70:71]
	v_mul_f32_e32 v56, v61, v61
	v_mul_f32_e32 v57, v63, v63
	v_fmac_f32_e32 v56, v60, v60
	v_fmac_f32_e32 v57, v62, v62
	v_add_f32_e32 v56, v56, v57
	v_mul_f32_e32 v57, v59, v59
	v_mul_f32_e32 v68, v67, v67
	v_fmac_f32_e32 v57, v58, v58
	v_fmac_f32_e32 v68, v66, v66
	v_lshlrev_b32_e32 v74, 16, v136
	v_and_b32_e32 v75, 0xffff0000, v136
	v_lshlrev_b32_e32 v76, 16, v137
	v_and_b32_e32 v77, 0xffff0000, v137
	v_add_f32_e32 v57, v57, v68
	v_lshlrev_b32_e32 v80, 16, v139
	v_and_b32_e32 v81, 0xffff0000, v139
	v_add_f32_e32 v68, v56, v57
	v_cvt_pk_bf16_f32 v56, v60, v61
	v_cvt_pk_bf16_f32 v57, v62, v63
	v_pk_add_f32 v[54:55], v[54:55], v[76:77]
	v_pk_add_f32 v[52:53], v[52:53], v[74:75]
	v_lshlrev_b32_e32 v78, 16, v138
	v_and_b32_e32 v79, 0xffff0000, v138
	v_cvt_pk_bf16_f32 v58, v58, v59
	v_cvt_pk_bf16_f32 v59, v66, v67
	global_store_dwordx4 v[194:195], v[56:59], off sc1
	s_nop 1
	v_pk_add_f32 v[56:57], v[50:51], v[80:81]
	v_mul_f32_e32 v50, v53, v53
	v_mul_f32_e32 v51, v55, v55
	v_pk_add_f32 v[48:49], v[48:49], v[78:79]
	v_fmac_f32_e32 v50, v52, v52
	v_fmac_f32_e32 v51, v54, v54
	v_add_f32_e32 v50, v50, v51
	v_mul_f32_e32 v51, v49, v49
	v_mul_f32_e32 v58, v57, v57
	v_fmac_f32_e32 v51, v48, v48
	v_fmac_f32_e32 v58, v56, v56
	v_add_f32_e32 v51, v51, v58
	v_add_f32_e32 v50, v50, v51
	v_add_f32_e32 v58, v68, v50
	ds_bpermute_b32 v59, v120, v58
	v_cvt_pk_bf16_f32 v50, v52, v53
	v_cvt_pk_bf16_f32 v52, v48, v49
	s_waitcnt lgkmcnt(1)
	v_lshl_add_u64 v[64:65], v[194:195], 0, s[14:15]
	v_cvt_pk_bf16_f32 v51, v54, v55
	s_waitcnt lgkmcnt(0)
	v_add_f32_e32 v48, v58, v59
	ds_bpermute_b32 v49, v121, v48
	v_cvt_pk_bf16_f32 v53, v56, v57
	global_store_dwordx4 v[64:65], v[50:53], off sc1
	s_nop 1
	s_and_saveexec_b64 s[0:1], s[6:7]
	s_cbranch_execz .LBB0_2677
	s_waitcnt lgkmcnt(0)
	v_add_f32_e32 v50, v48, v49
	s_lshl_b32 s24, s45, 2
	v_lshlrev_b64 v[48:49], 6, v[192:193]
	s_ashr_i32 s25, s24, 31
	v_lshl_add_u64 v[48:49], s[16:17], 0, v[48:49]
	v_lshl_add_u64 v[48:49], s[24:25], 2, v[48:49]
	s_lshl_b32 s4, s40, 2
	v_lshl_add_u64 v[48:49], v[48:49], 0, s[4:5]
	global_store_dword v[48:49], v50, off

.LBB0_2679:
	s_or_b64 exec, exec, s[0:1]
	s_waitcnt vmcnt(14)
	v_lshlrev_b32_e32 v34, 16, v108
	v_and_b32_e32 v35, 0xffff0000, v108
	v_lshlrev_b32_e32 v36, 16, v109
	v_and_b32_e32 v37, 0xffff0000, v109
	v_lshlrev_b32_e32 v38, 16, v110
	v_and_b32_e32 v39, 0xffff0000, v110
	v_lshlrev_b32_e32 v40, 16, v111
	v_and_b32_e32 v41, 0xffff0000, v111
	v_pk_add_f32 v[30:31], v[30:31], v[36:37]
	v_pk_add_f32 v[28:29], v[28:29], v[34:35]
	v_pk_add_f32 v[34:35], v[26:27], v[40:41]
	v_pk_add_f32 v[26:27], v[24:25], v[38:39]
	v_mul_f32_e32 v24, v29, v29
	v_mul_f32_e32 v25, v31, v31
	v_fmac_f32_e32 v24, v28, v28
	v_fmac_f32_e32 v25, v30, v30
	v_add_f32_e32 v24, v24, v25
	v_mul_f32_e32 v25, v27, v27
	v_mul_f32_e32 v36, v35, v35
	v_fmac_f32_e32 v25, v26, v26
	v_fmac_f32_e32 v36, v34, v34
	s_waitcnt vmcnt(14)
	v_lshlrev_b32_e32 v42, 16, v104
	v_and_b32_e32 v43, 0xffff0000, v104
	v_lshlrev_b32_e32 v44, 16, v105
	v_and_b32_e32 v45, 0xffff0000, v105
	v_add_f32_e32 v25, v25, v36
	v_lshlrev_b32_e32 v48, 16, v107
	v_and_b32_e32 v49, 0xffff0000, v107
	v_add_f32_e32 v36, v24, v25
	v_cvt_pk_bf16_f32 v24, v28, v29
	v_cvt_pk_bf16_f32 v25, v30, v31
	v_pk_add_f32 v[22:23], v[22:23], v[44:45]
	v_pk_add_f32 v[20:21], v[20:21], v[42:43]
	v_lshlrev_b32_e32 v46, 16, v106
	v_and_b32_e32 v47, 0xffff0000, v106
	v_cvt_pk_bf16_f32 v26, v26, v27
	v_cvt_pk_bf16_f32 v27, v34, v35
	global_store_dwordx4 v[118:119], v[24:27], off sc1
	s_nop 1
	v_pk_add_f32 v[24:25], v[18:19], v[48:49]
	v_mul_f32_e32 v18, v21, v21
	v_mul_f32_e32 v19, v23, v23
	v_pk_add_f32 v[16:17], v[16:17], v[46:47]
	v_fmac_f32_e32 v18, v20, v20
	v_fmac_f32_e32 v19, v22, v22
	v_add_f32_e32 v18, v18, v19
	v_mul_f32_e32 v19, v17, v17
	v_mul_f32_e32 v26, v25, v25
	v_fmac_f32_e32 v19, v16, v16
	v_fmac_f32_e32 v26, v24, v24
	v_add_f32_e32 v19, v19, v26
	v_add_f32_e32 v18, v18, v19
	v_add_f32_e32 v26, v36, v18
	ds_bpermute_b32 v27, v120, v26
	v_cvt_pk_bf16_f32 v18, v20, v21
	v_cvt_pk_bf16_f32 v20, v16, v17
	s_waitcnt lgkmcnt(1)
	v_lshl_add_u64 v[32:33], v[118:119], 0, s[14:15]
	v_cvt_pk_bf16_f32 v19, v22, v23
	s_waitcnt lgkmcnt(0)
	v_add_f32_e32 v16, v26, v27
	ds_bpermute_b32 v17, v121, v16
	v_cvt_pk_bf16_f32 v21, v24, v25
	global_store_dwordx4 v[32:33], v[18:21], off sc1
	s_nop 1
	s_and_saveexec_b64 s[0:1], s[6:7]
	s_cbranch_execz .LBB0_2681
	s_waitcnt lgkmcnt(0)
	v_add_f32_e32 v18, v16, v17
	s_lshl_b32 s24, s45, 2
	v_lshlrev_b64 v[16:17], 6, v[116:117]
	s_ashr_i32 s25, s24, 31
	v_lshl_add_u64 v[16:17], s[16:17], 0, v[16:17]
	v_lshl_add_u64 v[16:17], s[24:25], 2, v[16:17]
	s_lshl_b32 s4, s40, 2
	v_lshl_add_u64 v[16:17], v[16:17], 0, s[4:5]
	global_store_dword v[16:17], v18, off
.LBB0_2681:
	s_or_b64 exec, exec, s[0:1]
	s_waitcnt vmcnt(15)
	v_lshlrev_b32_e32 v18, 16, v100
	v_and_b32_e32 v19, 0xffff0000, v100
	v_lshlrev_b32_e32 v20, 16, v101
	v_and_b32_e32 v21, 0xffff0000, v101
	v_lshlrev_b32_e32 v22, 16, v102
	v_and_b32_e32 v23, 0xffff0000, v102
	v_lshlrev_b32_e32 v24, 16, v103
	v_and_b32_e32 v25, 0xffff0000, v103
	v_pk_add_f32 v[14:15], v[14:15], v[20:21]
	v_pk_add_f32 v[12:13], v[12:13], v[18:19]
	v_pk_add_f32 v[18:19], v[10:11], v[24:25]
	v_pk_add_f32 v[10:11], v[8:9], v[22:23]
	v_mul_f32_e32 v8, v13, v13
	v_mul_f32_e32 v9, v15, v15
	v_fmac_f32_e32 v8, v12, v12
	v_fmac_f32_e32 v9, v14, v14
	v_add_f32_e32 v8, v8, v9
	v_mul_f32_e32 v9, v11, v11
	v_mul_f32_e32 v20, v19, v19
	v_fmac_f32_e32 v9, v10, v10
	v_fmac_f32_e32 v20, v18, v18
	s_waitcnt vmcnt(15)
	v_lshlrev_b32_e32 v26, 16, v96
	v_and_b32_e32 v27, 0xffff0000, v96
	v_lshlrev_b32_e32 v28, 16, v97
	v_and_b32_e32 v29, 0xffff0000, v97
	v_add_f32_e32 v9, v9, v20
	v_lshlrev_b32_e32 v32, 16, v99
	v_and_b32_e32 v33, 0xffff0000, v99
	v_add_f32_e32 v20, v8, v9
	v_cvt_pk_bf16_f32 v8, v12, v13
	v_cvt_pk_bf16_f32 v9, v14, v15
	v_pk_add_f32 v[6:7], v[6:7], v[28:29]
	v_pk_add_f32 v[4:5], v[4:5], v[26:27]
	v_lshlrev_b32_e32 v30, 16, v98
	v_and_b32_e32 v31, 0xffff0000, v98
	v_cvt_pk_bf16_f32 v10, v10, v11
	v_cvt_pk_bf16_f32 v11, v18, v19
	global_store_dwordx4 v[114:115], v[8:11], off sc1
	s_nop 1
	v_pk_add_f32 v[8:9], v[2:3], v[32:33]
	v_mul_f32_e32 v2, v5, v5
	v_mul_f32_e32 v3, v7, v7
	v_pk_add_f32 v[0:1], v[0:1], v[30:31]
	v_fmac_f32_e32 v2, v4, v4
	v_fmac_f32_e32 v3, v6, v6
	v_add_f32_e32 v2, v2, v3
	v_mul_f32_e32 v3, v1, v1
	v_mul_f32_e32 v10, v9, v9
	v_fmac_f32_e32 v3, v0, v0
	v_fmac_f32_e32 v10, v8, v8
	v_add_f32_e32 v3, v3, v10
	v_add_f32_e32 v2, v2, v3
	v_add_f32_e32 v10, v20, v2
	ds_bpermute_b32 v11, v120, v10
	v_cvt_pk_bf16_f32 v2, v4, v5
	v_cvt_pk_bf16_f32 v4, v0, v1
	s_waitcnt lgkmcnt(1)
	v_lshl_add_u64 v[16:17], v[114:115], 0, s[14:15]
	v_cvt_pk_bf16_f32 v3, v6, v7
	s_waitcnt lgkmcnt(0)
	v_add_f32_e32 v0, v10, v11
	ds_bpermute_b32 v1, v121, v0
	v_cvt_pk_bf16_f32 v5, v8, v9
	global_store_dwordx4 v[16:17], v[2:5], off sc1
	s_nop 1
	s_and_saveexec_b64 s[0:1], s[6:7]
	s_cbranch_execz .LBB0_2683
	s_waitcnt lgkmcnt(0)
	v_add_f32_e32 v2, v0, v1
	s_lshl_b32 s24, s45, 2
	v_lshlrev_b64 v[0:1], 6, v[112:113]
	s_ashr_i32 s25, s24, 31
	v_lshl_add_u64 v[0:1], s[16:17], 0, v[0:1]
	v_lshl_add_u64 v[0:1], s[24:25], 2, v[0:1]
	s_lshl_b32 s4, s40, 2
	v_lshl_add_u64 v[0:1], v[0:1], 0, s[4:5]
	global_store_dword v[0:1], v2, off

.LBB0_2877:
	v_lshl_add_u32 v200, s24, 8, v169
	v_lshl_or_b32 v128, s45, 8, v211
	v_ashrrev_i32_e32 v201, 31, v200
	v_lshlrev_b64 v[130:131], 11, v[200:201]
	v_ashrrev_i32_e32 v129, 31, v128
	v_lshl_add_u64 v[130:131], s[12:13], 0, v[130:131]
	v_lshlrev_b64 v[202:203], 1, v[128:129]
	v_lshl_add_u64 v[224:225], v[130:131], 0, v[202:203]
	global_load_dwordx4 v[216:219], v[224:225], off
	global_load_dwordx4 v[220:223], v[224:225], off offset:256
	v_or_b32_e32 v206, 16, v200
	v_or_b32_e32 v198, 32, v200
	v_or_b32_e32 v194, 48, v200
	v_add_u32_e32 v190, 0x80, v200
	v_add_u32_e32 v186, 0x90, v200
	v_ashrrev_i32_e32 v207, 31, v206
	v_ashrrev_i32_e32 v199, 31, v198
	v_ashrrev_i32_e32 v195, 31, v194
	v_ashrrev_i32_e32 v191, 31, v190
	v_ashrrev_i32_e32 v187, 31, v186
	v_lshlrev_b64 v[128:129], 11, v[206:207]
	v_lshlrev_b64 v[130:131], 11, v[198:199]
	v_lshlrev_b64 v[132:133], 11, v[194:195]
	v_lshlrev_b64 v[134:135], 11, v[190:191]
	v_lshlrev_b64 v[136:137], 11, v[186:187]
	v_lshl_add_u64 v[128:129], s[12:13], 0, v[128:129]
	v_lshl_add_u64 v[130:131], s[12:13], 0, v[130:131]
	v_lshl_add_u64 v[132:133], s[12:13], 0, v[132:133]
	v_lshl_add_u64 v[134:135], s[12:13], 0, v[134:135]
	v_lshl_add_u64 v[136:137], s[12:13], 0, v[136:137]
	v_lshl_add_u64 v[208:209], v[128:129], 0, v[202:203]
	v_lshl_add_u64 v[204:205], v[130:131], 0, v[202:203]
	v_lshl_add_u64 v[196:197], v[132:133], 0, v[202:203]
	v_lshl_add_u64 v[192:193], v[134:135], 0, v[202:203]
	v_lshl_add_u64 v[188:189], v[136:137], 0, v[202:203]
	global_load_dwordx4 v[164:167], v[208:209], off
	global_load_dwordx4 v[160:163], v[208:209], off offset:256
	global_load_dwordx4 v[156:159], v[204:205], off
	global_load_dwordx4 v[152:155], v[204:205], off offset:256
	global_load_dwordx4 v[148:151], v[196:197], off
	global_load_dwordx4 v[144:147], v[196:197], off offset:256
	global_load_dwordx4 v[140:143], v[192:193], off
	global_load_dwordx4 v[136:139], v[192:193], off offset:256
	global_load_dwordx4 v[132:135], v[188:189], off
	global_load_dwordx4 v[128:131], v[188:189], off offset:256
	v_lshl_add_u64 v[226:227], v[224:225], 0, s[14:15]
	s_waitcnt vmcnt(8)
	v_lshlrev_b32_e32 v228, 16, v216
	v_and_b32_e32 v229, 0xffff0000, v216
	v_lshlrev_b32_e32 v216, 16, v217
	v_and_b32_e32 v217, 0xffff0000, v217
	v_lshlrev_b32_e32 v230, 16, v218
	v_and_b32_e32 v231, 0xffff0000, v218
	v_lshlrev_b32_e32 v218, 16, v219
	v_and_b32_e32 v219, 0xffff0000, v219
	v_lshlrev_b32_e32 v232, 16, v220
	v_and_b32_e32 v233, 0xffff0000, v220
	v_lshlrev_b32_e32 v220, 16, v221
	v_and_b32_e32 v221, 0xffff0000, v221
	v_lshlrev_b32_e32 v234, 16, v222
	v_and_b32_e32 v235, 0xffff0000, v222
	v_lshlrev_b32_e32 v222, 16, v223
	v_and_b32_e32 v223, 0xffff0000, v223
	v_pk_add_f32 v[126:127], v[126:127], v[216:217]
	v_pk_add_f32 v[124:125], v[124:125], v[228:229]
	v_pk_add_f32 v[122:123], v[122:123], v[218:219]
	v_pk_add_f32 v[120:121], v[120:121], v[230:231]
	v_pk_add_f32 v[118:119], v[118:119], v[220:221]
	v_pk_add_f32 v[216:217], v[114:115], v[222:223]
	v_mul_f32_e32 v220, v125, v125
	v_mul_f32_e32 v221, v127, v127
	v_mul_f32_e32 v222, v121, v121
	v_mul_f32_e32 v223, v123, v123
	v_pk_add_f32 v[218:219], v[112:113], v[234:235]
	v_cvt_pk_bf16_f32 v112, v124, v125
	v_cvt_pk_bf16_f32 v113, v126, v127
	v_fmac_f32_e32 v220, v124, v124
	v_fmac_f32_e32 v221, v126, v126
	v_fmac_f32_e32 v222, v120, v120
	v_fmac_f32_e32 v223, v122, v122
	v_pk_add_f32 v[116:117], v[116:117], v[232:233]
	v_cvt_pk_bf16_f32 v114, v120, v121
	v_cvt_pk_bf16_f32 v115, v122, v123
	global_store_dwordx4 v[224:225], v[112:115], off sc1
	s_nop 1
	v_add_f32_e32 v112, v220, v221
	v_add_f32_e32 v113, v222, v223
	v_mul_f32_e32 v121, v117, v117
	v_mul_f32_e32 v123, v119, v119
	v_add_f32_e32 v112, v112, v113
	v_mul_f32_e32 v113, v219, v219
	v_mul_f32_e32 v115, v217, v217
	v_fmac_f32_e32 v121, v116, v116
	v_fmac_f32_e32 v123, v118, v118
	v_fmac_f32_e32 v113, v218, v218
	v_fmac_f32_e32 v115, v216, v216
	v_add_f32_e32 v114, v121, v123
	v_add_f32_e32 v113, v113, v115
	v_add_f32_e32 v113, v114, v113
	v_and_b32_e32 v114, 64, v215
	v_add_f32_e32 v112, v112, v113
	v_xor_b32_e32 v113, 16, v215
	v_add_u32_e32 v121, 64, v114
	v_cmp_lt_i32_e32 vcc, v113, v121
	v_cvt_pk_bf16_f32 v114, v116, v117
	v_cvt_pk_bf16_f32 v115, v118, v119
	v_cndmask_b32_e32 v113, v215, v113, vcc
	v_lshlrev_b32_e32 v120, 2, v113
	ds_bpermute_b32 v113, v120, v112
	v_cvt_pk_bf16_f32 v116, v218, v219
	v_cvt_pk_bf16_f32 v117, v216, v217
	global_store_dwordx4 v[226:227], v[114:117], off sc1
	s_nop 1
	s_waitcnt lgkmcnt(0)
	v_add_f32_e32 v112, v112, v113
	v_xor_b32_e32 v113, 32, v215
	v_cmp_lt_i32_e32 vcc, v113, v121
	s_nop 1
	v_cndmask_b32_e32 v113, v215, v113, vcc
	v_lshlrev_b32_e32 v121, 2, v113
	ds_bpermute_b32 v113, v121, v112
	s_and_saveexec_b64 s[0:1], s[6:7]
	s_cbranch_execz .LBB0_2879
	s_waitcnt lgkmcnt(0)
	v_add_f32_e32 v114, v112, v113
	s_lshl_b32 s24, s45, 2
	v_lshlrev_b64 v[112:113], 6, v[200:201]
	s_ashr_i32 s25, s24, 31
	v_lshl_add_u64 v[112:113], s[16:17], 0, v[112:113]
	v_lshl_add_u64 v[112:113], s[24:25], 2, v[112:113]
	s_lshl_b32 s4, s40, 2
	v_lshl_add_u64 v[112:113], v[112:113], 0, s[4:5]
	global_store_dword v[112:113], v114, off

.LBB0_2881:
	s_or_b64 exec, exec, s[0:1]
	v_add_u32_e32 v116, 0xa0, v200
	v_ashrrev_i32_e32 v117, 31, v116
	s_waitcnt lgkmcnt(0)
	v_lshlrev_b64 v[96:97], 11, v[116:117]
	v_add_u32_e32 v112, 0xb0, v200
	v_lshl_add_u64 v[96:97], s[12:13], 0, v[96:97]
	v_ashrrev_i32_e32 v113, 31, v112
	v_lshl_add_u64 v[118:119], v[96:97], 0, v[202:203]
	v_lshlrev_b64 v[96:97], 11, v[112:113]
	v_lshl_add_u64 v[96:97], s[12:13], 0, v[96:97]
	v_lshl_add_u64 v[114:115], v[96:97], 0, v[202:203]
	global_load_dwordx4 v[108:111], v[118:119], off
	global_load_dwordx4 v[104:107], v[118:119], off offset:256
	global_load_dwordx4 v[100:103], v[114:115], off
	global_load_dwordx4 v[96:99], v[114:115], off offset:256
	s_waitcnt vmcnt(14)
	v_lshlrev_b32_e32 v124, 16, v156
	v_and_b32_e32 v125, 0xffff0000, v156
	v_lshlrev_b32_e32 v126, 16, v157
	v_and_b32_e32 v127, 0xffff0000, v157
	v_lshlrev_b32_e32 v156, 16, v158
	v_and_b32_e32 v157, 0xffff0000, v158
	v_lshlrev_b32_e32 v158, 16, v159
	v_and_b32_e32 v159, 0xffff0000, v159
	v_pk_add_f32 v[94:95], v[94:95], v[126:127]
	v_pk_add_f32 v[92:93], v[92:93], v[124:125]
	v_pk_add_f32 v[124:125], v[90:91], v[158:159]
	v_pk_add_f32 v[90:91], v[88:89], v[156:157]
	v_mul_f32_e32 v88, v93, v93
	v_mul_f32_e32 v89, v95, v95
	v_fmac_f32_e32 v88, v92, v92
	v_fmac_f32_e32 v89, v94, v94
	v_add_f32_e32 v88, v88, v89
	v_mul_f32_e32 v89, v91, v91
	v_mul_f32_e32 v126, v125, v125
	v_fmac_f32_e32 v89, v90, v90
	v_fmac_f32_e32 v126, v124, v124
	v_lshlrev_b32_e32 v160, 16, v152
	v_and_b32_e32 v161, 0xffff0000, v152
	v_lshlrev_b32_e32 v152, 16, v153
	v_and_b32_e32 v153, 0xffff0000, v153
	v_add_f32_e32 v89, v89, v126
	v_lshlrev_b32_e32 v162, 16, v154
	v_and_b32_e32 v163, 0xffff0000, v154
	v_lshlrev_b32_e32 v154, 16, v155
	v_and_b32_e32 v155, 0xffff0000, v155
	v_add_f32_e32 v126, v88, v89
	v_cvt_pk_bf16_f32 v88, v92, v93
	v_cvt_pk_bf16_f32 v89, v94, v95
	v_pk_add_f32 v[86:87], v[86:87], v[152:153]
	v_pk_add_f32 v[84:85], v[84:85], v[160:161]
	v_cvt_pk_bf16_f32 v90, v90, v91
	v_cvt_pk_bf16_f32 v91, v124, v125
	global_store_dwordx4 v[204:205], v[88:91], off sc1
	s_nop 1
	v_pk_add_f32 v[88:89], v[82:83], v[154:155]
	v_mul_f32_e32 v82, v85, v85
	v_mul_f32_e32 v83, v87, v87
	v_pk_add_f32 v[80:81], v[80:81], v[162:163]
	v_fmac_f32_e32 v82, v84, v84
	v_fmac_f32_e32 v83, v86, v86
	v_add_f32_e32 v82, v82, v83
	v_mul_f32_e32 v83, v81, v81
	v_mul_f32_e32 v90, v89, v89
	v_fmac_f32_e32 v83, v80, v80
	v_fmac_f32_e32 v90, v88, v88
	v_add_f32_e32 v83, v83, v90
	v_add_f32_e32 v82, v82, v83
	v_add_f32_e32 v90, v126, v82
	ds_bpermute_b32 v91, v120, v90
	v_cvt_pk_bf16_f32 v82, v84, v85
	v_cvt_pk_bf16_f32 v84, v80, v81
	v_lshl_add_u64 v[122:123], v[204:205], 0, s[14:15]
	v_cvt_pk_bf16_f32 v83, v86, v87
	s_waitcnt lgkmcnt(0)
	v_add_f32_e32 v80, v90, v91
	ds_bpermute_b32 v81, v121, v80
	v_cvt_pk_bf16_f32 v85, v88, v89
	global_store_dwordx4 v[122:123], v[82:85], off sc1
	s_nop 1
	s_and_saveexec_b64 s[0:1], s[6:7]
	s_cbranch_execz .LBB0_2883
	s_waitcnt lgkmcnt(0)
	v_add_f32_e32 v82, v80, v81
	s_lshl_b32 s24, s45, 2
	v_lshlrev_b64 v[80:81], 6, v[198:199]
	s_ashr_i32 s25, s24, 31
	v_lshl_add_u64 v[80:81], s[16:17], 0, v[80:81]
	v_lshl_add_u64 v[80:81], s[24:25], 2, v[80:81]
	s_lshl_b32 s4, s40, 2
	v_lshl_add_u64 v[80:81], v[80:81], 0, s[4:5]
	global_store_dword v[80:81], v82, off

.LBB0_2885:
	s_or_b64 exec, exec, s[0:1]
	s_waitcnt vmcnt(16)
	v_lshlrev_b32_e32 v66, 16, v140
	v_and_b32_e32 v67, 0xffff0000, v140
	v_lshlrev_b32_e32 v68, 16, v141
	v_and_b32_e32 v69, 0xffff0000, v141
	v_lshlrev_b32_e32 v70, 16, v142
	v_and_b32_e32 v71, 0xffff0000, v142
	v_lshlrev_b32_e32 v72, 16, v143
	v_and_b32_e32 v73, 0xffff0000, v143
	v_pk_add_f32 v[62:63], v[62:63], v[68:69]
	v_pk_add_f32 v[60:61], v[60:61], v[66:67]
	v_pk_add_f32 v[66:67], v[58:59], v[72:73]
	v_pk_add_f32 v[58:59], v[56:57], v[70:71]
	v_mul_f32_e32 v56, v61, v61
	v_mul_f32_e32 v57, v63, v63
	v_fmac_f32_e32 v56, v60, v60
	v_fmac_f32_e32 v57, v62, v62
	v_add_f32_e32 v56, v56, v57
	v_mul_f32_e32 v57, v59, v59
	v_mul_f32_e32 v68, v67, v67
	v_fmac_f32_e32 v57, v58, v58
	v_fmac_f32_e32 v68, v66, v66
	v_lshlrev_b32_e32 v74, 16, v136
	v_and_b32_e32 v75, 0xffff0000, v136
	v_lshlrev_b32_e32 v76, 16, v137
	v_and_b32_e32 v77, 0xffff0000, v137
	v_add_f32_e32 v57, v57, v68
	v_lshlrev_b32_e32 v80, 16, v139
	v_and_b32_e32 v81, 0xffff0000, v139
	v_add_f32_e32 v68, v56, v57
	v_cvt_pk_bf16_f32 v56, v60, v61
	v_cvt_pk_bf16_f32 v57, v62, v63
	v_pk_add_f32 v[54:55], v[54:55], v[76:77]
	v_pk_add_f32 v[52:53], v[52:53], v[74:75]
	v_lshlrev_b32_e32 v78, 16, v138
	v_and_b32_e32 v79, 0xffff0000, v138
	v_cvt_pk_bf16_f32 v58, v58, v59
	v_cvt_pk_bf16_f32 v59, v66, v67
	global_store_dwordx4 v[192:193], v[56:59], off sc1
	s_nop 1
	v_pk_add_f32 v[56:57], v[50:51], v[80:81]
	v_mul_f32_e32 v50, v53, v53
	v_mul_f32_e32 v51, v55, v55
	v_pk_add_f32 v[48:49], v[48:49], v[78:79]
	v_fmac_f32_e32 v50, v52, v52
	v_fmac_f32_e32 v51, v54, v54
	v_add_f32_e32 v50, v50, v51
	v_mul_f32_e32 v51, v49, v49
	v_mul_f32_e32 v58, v57, v57
	v_fmac_f32_e32 v51, v48, v48
	v_fmac_f32_e32 v58, v56, v56
	v_add_f32_e32 v51, v51, v58
	v_add_f32_e32 v50, v50, v51
	v_add_f32_e32 v58, v68, v50
	ds_bpermute_b32 v59, v120, v58
	v_cvt_pk_bf16_f32 v50, v52, v53
	v_cvt_pk_bf16_f32 v52, v48, v49
	s_waitcnt lgkmcnt(1)
	v_lshl_add_u64 v[64:65], v[192:193], 0, s[14:15]
	v_cvt_pk_bf16_f32 v51, v54, v55
	s_waitcnt lgkmcnt(0)
	v_add_f32_e32 v48, v58, v59
	ds_bpermute_b32 v49, v121, v48
	v_cvt_pk_bf16_f32 v53, v56, v57
	global_store_dwordx4 v[64:65], v[50:53], off sc1
	s_nop 1
	s_and_saveexec_b64 s[0:1], s[6:7]
	s_cbranch_execz .LBB0_2887
	s_waitcnt lgkmcnt(0)
	v_add_f32_e32 v50, v48, v49
	s_lshl_b32 s24, s45, 2
	v_lshlrev_b64 v[48:49], 6, v[190:191]
	s_ashr_i32 s25, s24, 31
	v_lshl_add_u64 v[48:49], s[16:17], 0, v[48:49]
	v_lshl_add_u64 v[48:49], s[24:25], 2, v[48:49]
	s_lshl_b32 s4, s40, 2
	v_lshl_add_u64 v[48:49], v[48:49], 0, s[4:5]
	global_store_dword v[48:49], v50, off
